# gdn1 conv-input loads of the k and v matrices issued with the q matrix loads (spare registers, counted waits)
# speedup vs baseline: 1.0037x; 1.0037x over previous
.LBB0_607:
	s_or_b64 exec, exec, s[6:7]
	v_or_b32_e32 v174, 0x100, v50
	v_lshlrev_b32_e32 v174, 1, v174
	v_mov_b32_e32 v175, 0
	v_or_b32_e32 v176, 0x200, v50
	v_lshlrev_b32_e32 v176, 1, v176
	v_mov_b32_e32 v177, 0
	v_mov_b64_e32 v[172:173], s[8:9]
	v_mad_i64_i32 v[172:173], s[64:65], v51, s33, v[172:173]
	v_lshl_add_u64 v[172:173], v[172:173], 0, v[174:175]
	global_load_ushort v134, v[172:173], off offset:2048
	v_mov_b64_e32 v[172:173], s[8:9]
	v_mad_i64_i32 v[172:173], s[64:65], v52, s33, v[172:173]
	v_lshl_add_u64 v[172:173], v[172:173], 0, v[174:175]
	global_load_ushort v135, v[172:173], off offset:2048
	v_mov_b64_e32 v[172:173], s[8:9]
	v_mad_i64_i32 v[172:173], s[64:65], v53, s33, v[172:173]
	v_lshl_add_u64 v[172:173], v[172:173], 0, v[174:175]
	global_load_ushort v136, v[172:173], off offset:2048
	v_mov_b64_e32 v[172:173], s[8:9]
	v_mad_i64_i32 v[172:173], s[64:65], v54, s33, v[172:173]
	v_lshl_add_u64 v[172:173], v[172:173], 0, v[174:175]
	global_load_ushort v137, v[172:173], off offset:2048
	v_mov_b64_e32 v[172:173], s[8:9]
	v_mad_i64_i32 v[172:173], s[64:65], v55, s33, v[172:173]
	v_lshl_add_u64 v[172:173], v[172:173], 0, v[174:175]
	global_load_ushort v138, v[172:173], off offset:2048
	v_mov_b64_e32 v[172:173], s[8:9]
	v_mad_i64_i32 v[172:173], s[64:65], v56, s33, v[172:173]
	v_lshl_add_u64 v[172:173], v[172:173], 0, v[174:175]
	global_load_ushort v139, v[172:173], off offset:2048
	v_mov_b64_e32 v[172:173], s[8:9]
	v_mad_i64_i32 v[172:173], s[64:65], v57, s33, v[172:173]
	v_lshl_add_u64 v[172:173], v[172:173], 0, v[174:175]
	global_load_ushort v140, v[172:173], off offset:2048
	v_mov_b64_e32 v[172:173], s[8:9]
	v_mad_i64_i32 v[172:173], s[64:65], v58, s33, v[172:173]
	v_lshl_add_u64 v[172:173], v[172:173], 0, v[174:175]
	global_load_ushort v141, v[172:173], off offset:2048
	v_mov_b64_e32 v[172:173], s[8:9]
	v_mad_i64_i32 v[172:173], s[64:65], v59, s33, v[172:173]
	v_lshl_add_u64 v[172:173], v[172:173], 0, v[174:175]
	global_load_ushort v142, v[172:173], off offset:2048
	v_mov_b64_e32 v[172:173], s[8:9]
	v_mad_i64_i32 v[172:173], s[64:65], v60, s33, v[172:173]
	v_lshl_add_u64 v[172:173], v[172:173], 0, v[174:175]
	global_load_ushort v143, v[172:173], off offset:2048
	v_mov_b64_e32 v[172:173], s[8:9]
	v_mad_i64_i32 v[172:173], s[64:65], v61, s33, v[172:173]
	v_lshl_add_u64 v[172:173], v[172:173], 0, v[174:175]
	global_load_ushort v144, v[172:173], off offset:2048
	v_mov_b64_e32 v[172:173], s[8:9]
	v_mad_i64_i32 v[172:173], s[64:65], v62, s33, v[172:173]
	v_lshl_add_u64 v[172:173], v[172:173], 0, v[174:175]
	global_load_ushort v145, v[172:173], off offset:2048
	v_mov_b64_e32 v[172:173], s[8:9]
	v_mad_i64_i32 v[172:173], s[64:65], v63, s33, v[172:173]
	v_lshl_add_u64 v[172:173], v[172:173], 0, v[174:175]
	global_load_ushort v146, v[172:173], off offset:2048
	v_mov_b64_e32 v[172:173], s[8:9]
	v_mad_i64_i32 v[172:173], s[64:65], v64, s33, v[172:173]
	v_lshl_add_u64 v[172:173], v[172:173], 0, v[174:175]
	global_load_ushort v147, v[172:173], off offset:2048
	v_mov_b64_e32 v[172:173], s[8:9]
	v_mad_i64_i32 v[172:173], s[64:65], v65, s33, v[172:173]
	v_lshl_add_u64 v[172:173], v[172:173], 0, v[174:175]
	global_load_ushort v148, v[172:173], off offset:2048
	v_mov_b64_e32 v[172:173], s[8:9]
	v_mad_i64_i32 v[172:173], s[64:65], v66, s33, v[172:173]
	v_lshl_add_u64 v[172:173], v[172:173], 0, v[174:175]
	global_load_ushort v149, v[172:173], off offset:2048
	v_mov_b64_e32 v[172:173], s[8:9]
	v_mad_i64_i32 v[172:173], s[64:65], v67, s33, v[172:173]
	v_lshl_add_u64 v[172:173], v[172:173], 0, v[174:175]
	global_load_ushort v150, v[172:173], off offset:2048
	v_mov_b64_e32 v[172:173], s[8:9]
	v_mad_i64_i32 v[172:173], s[64:65], v68, s33, v[172:173]
	v_lshl_add_u64 v[172:173], v[172:173], 0, v[174:175]
	global_load_ushort v151, v[172:173], off offset:2048
	v_mov_b64_e32 v[172:173], s[8:9]
	v_mad_i64_i32 v[172:173], s[64:65], v69, s33, v[172:173]
	v_lshl_add_u64 v[172:173], v[172:173], 0, v[174:175]
	global_load_ushort v152, v[172:173], off offset:2048
	v_mov_b64_e32 v[172:173], s[8:9]
	v_mad_i64_i32 v[172:173], s[64:65], v51, s33, v[172:173]
	v_lshl_add_u64 v[172:173], v[172:173], 0, v[176:177]
	global_load_ushort v153, v[172:173], off offset:2048
	v_mov_b64_e32 v[172:173], s[8:9]
	v_mad_i64_i32 v[172:173], s[64:65], v52, s33, v[172:173]
	v_lshl_add_u64 v[172:173], v[172:173], 0, v[176:177]
	global_load_ushort v154, v[172:173], off offset:2048
	v_mov_b64_e32 v[172:173], s[8:9]
	v_mad_i64_i32 v[172:173], s[64:65], v53, s33, v[172:173]
	v_lshl_add_u64 v[172:173], v[172:173], 0, v[176:177]
	global_load_ushort v155, v[172:173], off offset:2048
	v_mov_b64_e32 v[172:173], s[8:9]
	v_mad_i64_i32 v[172:173], s[64:65], v54, s33, v[172:173]
	v_lshl_add_u64 v[172:173], v[172:173], 0, v[176:177]
	global_load_ushort v156, v[172:173], off offset:2048
	v_mov_b64_e32 v[172:173], s[8:9]
	v_mad_i64_i32 v[172:173], s[64:65], v55, s33, v[172:173]
	v_lshl_add_u64 v[172:173], v[172:173], 0, v[176:177]
	global_load_ushort v157, v[172:173], off offset:2048
	v_mov_b64_e32 v[172:173], s[8:9]
	v_mad_i64_i32 v[172:173], s[64:65], v56, s33, v[172:173]
	v_lshl_add_u64 v[172:173], v[172:173], 0, v[176:177]
	global_load_ushort v158, v[172:173], off offset:2048
	v_mov_b64_e32 v[172:173], s[8:9]
	v_mad_i64_i32 v[172:173], s[64:65], v57, s33, v[172:173]
	v_lshl_add_u64 v[172:173], v[172:173], 0, v[176:177]
	global_load_ushort v159, v[172:173], off offset:2048
	v_mov_b64_e32 v[172:173], s[8:9]
	v_mad_i64_i32 v[172:173], s[64:65], v58, s33, v[172:173]
	v_lshl_add_u64 v[172:173], v[172:173], 0, v[176:177]
	global_load_ushort v160, v[172:173], off offset:2048
	v_mov_b64_e32 v[172:173], s[8:9]
	v_mad_i64_i32 v[172:173], s[64:65], v59, s33, v[172:173]
	v_lshl_add_u64 v[172:173], v[172:173], 0, v[176:177]
	global_load_ushort v161, v[172:173], off offset:2048
	v_mov_b64_e32 v[172:173], s[8:9]
	v_mad_i64_i32 v[172:173], s[64:65], v60, s33, v[172:173]
	v_lshl_add_u64 v[172:173], v[172:173], 0, v[176:177]
	global_load_ushort v162, v[172:173], off offset:2048
	v_mov_b64_e32 v[172:173], s[8:9]
	v_mad_i64_i32 v[172:173], s[64:65], v61, s33, v[172:173]
	v_lshl_add_u64 v[172:173], v[172:173], 0, v[176:177]
	global_load_ushort v163, v[172:173], off offset:2048
	v_mov_b64_e32 v[172:173], s[8:9]
	v_mad_i64_i32 v[172:173], s[64:65], v62, s33, v[172:173]
	v_lshl_add_u64 v[172:173], v[172:173], 0, v[176:177]
	global_load_ushort v164, v[172:173], off offset:2048
	v_mov_b64_e32 v[172:173], s[8:9]
	v_mad_i64_i32 v[172:173], s[64:65], v63, s33, v[172:173]
	v_lshl_add_u64 v[172:173], v[172:173], 0, v[176:177]
	global_load_ushort v165, v[172:173], off offset:2048
	v_mov_b64_e32 v[172:173], s[8:9]
	v_mad_i64_i32 v[172:173], s[64:65], v64, s33, v[172:173]
	v_lshl_add_u64 v[172:173], v[172:173], 0, v[176:177]
	global_load_ushort v166, v[172:173], off offset:2048
	v_mov_b64_e32 v[172:173], s[8:9]
	v_mad_i64_i32 v[172:173], s[64:65], v65, s33, v[172:173]
	v_lshl_add_u64 v[172:173], v[172:173], 0, v[176:177]
	global_load_ushort v167, v[172:173], off offset:2048
	v_mov_b64_e32 v[172:173], s[8:9]
	v_mad_i64_i32 v[172:173], s[64:65], v66, s33, v[172:173]
	v_lshl_add_u64 v[172:173], v[172:173], 0, v[176:177]
	global_load_ushort v168, v[172:173], off offset:2048
	v_mov_b64_e32 v[172:173], s[8:9]
	v_mad_i64_i32 v[172:173], s[64:65], v67, s33, v[172:173]
	v_lshl_add_u64 v[172:173], v[172:173], 0, v[176:177]
	global_load_ushort v169, v[172:173], off offset:2048
	v_mov_b64_e32 v[172:173], s[8:9]
	v_mad_i64_i32 v[172:173], s[64:65], v68, s33, v[172:173]
	v_lshl_add_u64 v[172:173], v[172:173], 0, v[176:177]
	global_load_ushort v170, v[172:173], off offset:2048
	v_mov_b64_e32 v[172:173], s[8:9]
	v_mad_i64_i32 v[172:173], s[64:65], v69, s33, v[172:173]
	v_lshl_add_u64 v[172:173], v[172:173], 0, v[176:177]
	global_load_ushort v171, v[172:173], off offset:2048
	s_waitcnt vmcnt(38)
	v_lshlrev_b32_e32 v42, 16, v42
	v_lshlrev_b32_e32 v43, 16, v43
	v_lshlrev_b32_e32 v40, 16, v40
	v_lshlrev_b32_e32 v41, 16, v41
	v_lshlrev_b32_e32 v39, 16, v39
	v_lshlrev_b32_e32 v37, 16, v37
	v_lshlrev_b32_e32 v35, 16, v35
	v_lshlrev_b32_e32 v33, 16, v33
	v_lshlrev_b32_e32 v31, 16, v31
	v_lshlrev_b32_e32 v29, 16, v29
	v_lshlrev_b32_e32 v27, 16, v27
	v_lshlrev_b32_e32 v25, 16, v25
	v_lshlrev_b32_e32 v23, 16, v23
	v_lshlrev_b32_e32 v21, 16, v21
	v_lshlrev_b32_e32 v13, 16, v13
	v_lshlrev_b32_e32 v11, 16, v11
	v_lshlrev_b32_e32 v17, 16, v17
	v_lshlrev_b32_e32 v15, 16, v15
	v_lshlrev_b32_e32 v19, 16, v19
	v_pk_mul_f32 v[70:71], v[6:7], v[42:43]
	v_pk_mul_f32 v[44:45], v[8:9], v[40:41]
	v_add_f32_e32 v0, v70, v71
	v_add_f32_e32 v0, v0, v44
	v_add_f32_e32 v0, v0, v45
	v_mul_f32_e32 v5, 0xbfb8aa3b, v0
	v_exp_f32_e32 v5, v5
	s_ashr_i32 s17, s16, 31
	s_lshl_b64 s[6:7], s[16:17], 13
	s_add_u32 s43, s4, s6
	v_add_f32_e32 v5, 1.0, v5
	v_rcp_f32_e32 v5, v5
	s_addc_u32 s52, s5, s7
	v_mov_b32_e32 v42, v43
	v_mov_b32_e32 v43, v40
	v_mul_f32_e32 v0, v0, v5
	v_mul_f32_e32 v5, v0, v0
	v_mov_b32_e32 v38, v41
	v_pk_mul_f32 v[42:43], v[6:7], v[42:43]
	v_mov_b32_dpp v5, v5 quad_perm:[1,0,3,2] row_mask:0xf bank_mask:0xf bound_ctrl:1
	v_fmac_f32_e32 v5, v0, v0
	v_mov_b32_e32 v36, v39
	v_pk_mul_f32 v[40:41], v[6:7], v[40:41]
	v_add_f32_dpp v5, v5, v5 quad_perm:[2,3,0,1] row_mask:0xf bank_mask:0xf bound_ctrl:1
	v_mov_b32_e32 v34, v37
	v_mov_b32_e32 v32, v35
	v_add_f32_dpp v5, v5, v5 row_half_mirror row_mask:0xf bank_mask:0xf bound_ctrl:1
	v_mov_b32_e32 v30, v33
	v_mov_b32_e32 v28, v31
	v_add_f32_dpp v5, v5, v5 row_mirror row_mask:0xf bank_mask:0xf bound_ctrl:1
	v_mov_b32_e32 v26, v29
	v_readlane_b32 s64, v5, 16
	v_readlane_b32 s65, v5, 48
	v_readlane_b32 s6, v5, 0
	v_readlane_b32 s7, v5, 32
	v_mov_b32_e32 v44, s64
	v_mov_b32_e32 v45, s65
	v_pk_add_f32 v[44:45], s[6:7], v[44:45]
	s_add_u32 s6, s43, 0xbc27800
	v_add_f32_e32 v5, v44, v45
	v_add_f32_e32 v5, 0x358637bd, v5
	v_mul_f32_e32 v10, 0x4b800000, v5
	v_cmp_gt_f32_e32 vcc, s68, v5
	v_pk_mul_f32 v[44:45], v[8:9], v[38:39]
	s_movk_i32 s43, 0x900
	v_cndmask_b32_e32 v5, v5, v10, vcc
	v_rsq_f32_e32 v5, v5
	s_addc_u32 s7, s52, 0
	v_mul_lo_u32 v14, v49, s43
	v_lshl_add_u32 v10, v46, 1, 0
	v_mul_f32_e32 v12, 0x45800000, v5
	v_cndmask_b32_e32 v5, v5, v12, vcc
	v_mul_f32_e32 v5, 0x3e000000, v5
	v_mul_f32_e32 v0, v0, v5
	v_add_f32_e32 v5, v42, v43
	v_add_f32_e32 v5, v5, v44
	v_add_f32_e32 v5, v5, v45
	v_mul_f32_e32 v12, 0xbfb8aa3b, v5
	v_exp_f32_e32 v12, v12
	v_add_u32_e32 v43, v10, v14
	v_lshl_or_b32 v44, v49, 10, v46
	v_ashrrev_i32_e32 v45, 31, v44
	v_add_f32_e32 v12, 1.0, v12
	v_rcp_f32_e32 v12, v12
	v_cvt_pk_bf16_f32 v0, v0, s0
	v_lshl_add_u64 v[44:45], v[44:45], 1, s[6:7]
	global_store_short v[44:45], v0, off
	v_mul_f32_e32 v5, v5, v12
	v_mul_f32_e32 v12, v5, v5
	v_pk_mul_f32 v[44:45], v[8:9], v[36:37]
	ds_write_b16 v43, v0
	v_mov_b32_dpp v12, v12 quad_perm:[1,0,3,2] row_mask:0xf bank_mask:0xf bound_ctrl:1
	v_fmac_f32_e32 v12, v5, v5
	v_or_b32_e32 v0, 1, v48
	v_pk_mul_f32 v[38:39], v[6:7], v[38:39]
	v_add_f32_dpp v12, v12, v12 quad_perm:[2,3,0,1] row_mask:0xf bank_mask:0xf bound_ctrl:1
	v_pk_mul_f32 v[36:37], v[6:7], v[36:37]
	v_mov_b32_e32 v24, v27
	v_add_f32_dpp v12, v12, v12 row_half_mirror row_mask:0xf bank_mask:0xf bound_ctrl:1
	v_mov_b32_e32 v22, v25
	s_nop 0
	v_add_f32_dpp v12, v12, v12 row_mirror row_mask:0xf bank_mask:0xf bound_ctrl:1
	s_nop 0
	v_readlane_b32 s43, v12, 16
	v_readlane_b32 s52, v12, 48
	v_readlane_b32 s64, v12, 0
	v_readlane_b32 s65, v12, 32
	v_mov_b32_e32 v70, s43
	v_mov_b32_e32 v71, s52
	v_pk_add_f32 v[70:71], s[64:65], v[70:71]
	s_movk_i32 s43, 0x90
	v_add_f32_e32 v12, v70, v71
	v_add_f32_e32 v12, 0x358637bd, v12
	v_mul_f32_e32 v14, 0x4b800000, v12
	v_cmp_gt_f32_e32 vcc, s68, v12
	s_nop 1
	v_cndmask_b32_e32 v12, v12, v14, vcc
	v_rsq_f32_e32 v12, v12
	s_nop 0
	v_mul_f32_e32 v14, 0x45800000, v12
	v_cndmask_b32_e32 v12, v12, v14, vcc
	v_add_f32_e32 v14, v40, v41
	v_add_f32_e32 v14, v14, v44
	v_add_f32_e32 v14, v14, v45
	v_mul_f32_e32 v16, 0xbfb8aa3b, v14
	v_exp_f32_e32 v16, v16
	v_mul_f32_e32 v12, 0x3e000000, v12
	v_mul_f32_e32 v5, v5, v12
	v_mul_lo_u32 v12, v0, s43
	v_add_f32_e32 v16, 1.0, v16
	v_rcp_f32_e32 v16, v16
	v_lshl_or_b32 v40, v0, 6, v46
	v_ashrrev_i32_e32 v41, 31, v40
	v_cvt_pk_bf16_f32 v5, v5, s0
	v_mul_f32_e32 v0, v14, v16
	v_mul_f32_e32 v14, v0, v0
	v_add_u32_e32 v42, v10, v12
	v_lshl_add_u64 v[40:41], v[40:41], 1, s[6:7]
	v_mov_b32_dpp v14, v14 quad_perm:[1,0,3,2] row_mask:0xf bank_mask:0xf bound_ctrl:1
	v_fmac_f32_e32 v14, v0, v0
	ds_write_b16 v42, v5
	global_store_short v[40:41], v5, off
	v_add_f32_dpp v14, v14, v14 quad_perm:[2,3,0,1] row_mask:0xf bank_mask:0xf bound_ctrl:1
	v_pk_mul_f32 v[40:41], v[8:9], v[34:35]
	v_pk_mul_f32 v[34:35], v[6:7], v[34:35]
	v_add_f32_dpp v14, v14, v14 row_half_mirror row_mask:0xf bank_mask:0xf bound_ctrl:1
	v_add_u32_e32 v12, 0x2d0, v12
	s_nop 0
	v_add_f32_dpp v14, v14, v14 row_mirror row_mask:0xf bank_mask:0xf bound_ctrl:1
	s_nop 0
	v_readlane_b32 s43, v14, 16
	v_readlane_b32 s52, v14, 48
	v_readlane_b32 s64, v14, 0
	v_readlane_b32 s65, v14, 32
	v_mov_b32_e32 v44, s43
	v_mov_b32_e32 v45, s52
	v_pk_add_f32 v[44:45], s[64:65], v[44:45]
	s_nop 0
	v_add_f32_e32 v14, v44, v45
	v_add_f32_e32 v14, 0x358637bd, v14
	v_mul_f32_e32 v16, 0x4b800000, v14
	v_cmp_gt_f32_e32 vcc, s68, v14
	v_add_u32_e32 v44, v10, v12
	s_nop 0
	v_cndmask_b32_e32 v14, v14, v16, vcc
	v_rsq_f32_e32 v14, v14
	s_nop 0
	v_mul_f32_e32 v5, 0x45800000, v14
	v_cndmask_b32_e32 v5, v14, v5, vcc
	v_add_f32_e32 v14, v38, v39
	v_add_f32_e32 v14, v14, v40
	v_add_f32_e32 v14, v14, v41
	v_mul_f32_e32 v16, 0xbfb8aa3b, v14
	v_exp_f32_e32 v16, v16
	v_mul_f32_e32 v5, 0x3e000000, v5
	v_mul_f32_e32 v0, v0, v5
	v_cvt_pk_bf16_f32 v5, v0, s0
	v_add_f32_e32 v0, 1.0, v16
	v_rcp_f32_e32 v16, v0
	v_lshl_or_b32 v0, v48, 6, v46
	v_or_b32_e32 v38, 0x80, v0
	v_ashrrev_i32_e32 v39, 31, v38
	v_mul_f32_e32 v14, v14, v16
	v_mul_f32_e32 v16, v14, v14
	v_lshl_add_u64 v[38:39], v[38:39], 1, s[6:7]
	global_store_short v[38:39], v5, off
	v_mov_b32_dpp v16, v16 quad_perm:[1,0,3,2] row_mask:0xf bank_mask:0xf bound_ctrl:1
	v_fmac_f32_e32 v16, v14, v14
	v_pk_mul_f32 v[38:39], v[8:9], v[32:33]
	ds_write_b16 v42, v5 offset:144
	v_add_f32_dpp v16, v16, v16 quad_perm:[2,3,0,1] row_mask:0xf bank_mask:0xf bound_ctrl:1
	v_pk_mul_f32 v[32:33], v[6:7], v[32:33]
	s_nop 0
	v_add_f32_dpp v16, v16, v16 row_half_mirror row_mask:0xf bank_mask:0xf bound_ctrl:1
	s_nop 1
	v_add_f32_dpp v16, v16, v16 row_mirror row_mask:0xf bank_mask:0xf bound_ctrl:1
	s_nop 0
	v_readlane_b32 s43, v16, 16
	v_readlane_b32 s52, v16, 48
	v_readlane_b32 s64, v16, 0
	v_readlane_b32 s65, v16, 32
	v_mov_b32_e32 v40, s43
	v_mov_b32_e32 v41, s52
	v_pk_add_f32 v[40:41], s[64:65], v[40:41]
	s_nop 0
	v_add_f32_e32 v16, v40, v41
	v_add_f32_e32 v16, 0x358637bd, v16
	v_mul_f32_e32 v18, 0x4b800000, v16
	v_cmp_gt_f32_e32 vcc, s68, v16
	s_nop 1
	v_cndmask_b32_e32 v16, v16, v18, vcc
	v_add_f32_e32 v18, v36, v37
	v_rsq_f32_e32 v16, v16
	v_add_f32_e32 v18, v18, v38
	v_add_f32_e32 v18, v18, v39
	v_mul_f32_e32 v20, 0xbfb8aa3b, v18
	v_exp_f32_e32 v20, v20
	v_mul_f32_e32 v5, 0x45800000, v16
	v_cndmask_b32_e32 v5, v16, v5, vcc
	v_mul_f32_e32 v5, 0x3e000000, v5
	v_mul_f32_e32 v5, v14, v5
	v_add_f32_e32 v14, 1.0, v20
	v_rcp_f32_e32 v14, v14
	v_or_b32_e32 v36, 0xc0, v0
	v_ashrrev_i32_e32 v37, 31, v36
	v_cvt_pk_bf16_f32 v5, v5, s0
	v_mul_f32_e32 v14, v18, v14
	v_mul_f32_e32 v16, v14, v14
	v_lshl_add_u64 v[36:37], v[36:37], 1, s[6:7]
	global_store_short v[36:37], v5, off
	v_mov_b32_dpp v16, v16 quad_perm:[1,0,3,2] row_mask:0xf bank_mask:0xf bound_ctrl:1
	v_fmac_f32_e32 v16, v14, v14
	v_pk_mul_f32 v[36:37], v[8:9], v[30:31]
	ds_write_b16 v42, v5 offset:288
	v_add_f32_dpp v16, v16, v16 quad_perm:[2,3,0,1] row_mask:0xf bank_mask:0xf bound_ctrl:1
	v_pk_mul_f32 v[30:31], v[6:7], v[30:31]
	s_nop 0
	v_add_f32_dpp v16, v16, v16 row_half_mirror row_mask:0xf bank_mask:0xf bound_ctrl:1
	s_nop 1
	v_add_f32_dpp v16, v16, v16 row_mirror row_mask:0xf bank_mask:0xf bound_ctrl:1
	s_nop 0
	v_readlane_b32 s43, v16, 16
	v_readlane_b32 s52, v16, 48
	v_readlane_b32 s64, v16, 0
	v_readlane_b32 s65, v16, 32
	v_mov_b32_e32 v38, s43
	v_mov_b32_e32 v39, s52
	v_pk_add_f32 v[38:39], s[64:65], v[38:39]
	s_nop 0
	v_add_f32_e32 v16, v38, v39
	v_add_f32_e32 v16, 0x358637bd, v16
	v_mul_f32_e32 v18, 0x4b800000, v16
	v_cmp_gt_f32_e32 vcc, s68, v16
	s_nop 1
	v_cndmask_b32_e32 v16, v16, v18, vcc
	v_add_f32_e32 v18, v34, v35
	v_rsq_f32_e32 v16, v16
	v_add_f32_e32 v18, v18, v36
	v_add_f32_e32 v18, v18, v37
	v_mul_f32_e32 v20, 0xbfb8aa3b, v18
	v_exp_f32_e32 v20, v20
	v_mul_f32_e32 v5, 0x45800000, v16
	v_cndmask_b32_e32 v5, v16, v5, vcc
	v_mul_f32_e32 v5, 0x3e000000, v5
	v_mul_f32_e32 v5, v14, v5
	v_add_f32_e32 v14, 1.0, v20
	v_rcp_f32_e32 v14, v14
	v_or_b32_e32 v34, 0x100, v0
	v_ashrrev_i32_e32 v35, 31, v34
	v_cvt_pk_bf16_f32 v5, v5, s0
	v_mul_f32_e32 v14, v18, v14
	v_mul_f32_e32 v16, v14, v14
	v_lshl_add_u64 v[34:35], v[34:35], 1, s[6:7]
	global_store_short v[34:35], v5, off
	v_mov_b32_dpp v16, v16 quad_perm:[1,0,3,2] row_mask:0xf bank_mask:0xf bound_ctrl:1
	v_fmac_f32_e32 v16, v14, v14
	v_pk_mul_f32 v[34:35], v[8:9], v[28:29]
	ds_write_b16 v42, v5 offset:432
	v_add_f32_dpp v16, v16, v16 quad_perm:[2,3,0,1] row_mask:0xf bank_mask:0xf bound_ctrl:1
	v_pk_mul_f32 v[28:29], v[6:7], v[28:29]
	s_nop 0
	v_add_f32_dpp v16, v16, v16 row_half_mirror row_mask:0xf bank_mask:0xf bound_ctrl:1
	s_nop 1
	v_add_f32_dpp v16, v16, v16 row_mirror row_mask:0xf bank_mask:0xf bound_ctrl:1
	s_nop 0
	v_readlane_b32 s43, v16, 16
	v_readlane_b32 s52, v16, 48
	v_readlane_b32 s64, v16, 0
	v_readlane_b32 s65, v16, 32
	v_mov_b32_e32 v36, s43
	v_mov_b32_e32 v37, s52
	v_pk_add_f32 v[36:37], s[64:65], v[36:37]
	s_nop 0
	v_add_f32_e32 v16, v36, v37
	v_add_f32_e32 v16, 0x358637bd, v16
	v_mul_f32_e32 v18, 0x4b800000, v16
	v_cmp_gt_f32_e32 vcc, s68, v16
	s_nop 1
	v_cndmask_b32_e32 v16, v16, v18, vcc
	v_add_f32_e32 v18, v32, v33
	v_rsq_f32_e32 v16, v16
	v_add_f32_e32 v18, v18, v34
	v_add_f32_e32 v18, v18, v35
	v_mul_f32_e32 v20, 0xbfb8aa3b, v18
	v_exp_f32_e32 v20, v20
	v_mul_f32_e32 v5, 0x45800000, v16
	v_cndmask_b32_e32 v5, v16, v5, vcc
	v_mul_f32_e32 v5, 0x3e000000, v5
	v_mul_f32_e32 v5, v14, v5
	v_add_f32_e32 v14, 1.0, v20
	v_rcp_f32_e32 v14, v14
	v_or_b32_e32 v32, 0x140, v0
	v_ashrrev_i32_e32 v33, 31, v32
	v_cvt_pk_bf16_f32 v5, v5, s0
	v_mul_f32_e32 v14, v18, v14
	v_mul_f32_e32 v16, v14, v14
	v_lshl_add_u64 v[32:33], v[32:33], 1, s[6:7]
	ds_write_b16 v42, v5 offset:576
	v_mov_b32_dpp v16, v16 quad_perm:[1,0,3,2] row_mask:0xf bank_mask:0xf bound_ctrl:1
	v_fmac_f32_e32 v16, v14, v14
	global_store_short v[32:33], v5, off
	v_pk_mul_f32 v[32:33], v[8:9], v[26:27]
	v_add_f32_dpp v16, v16, v16 quad_perm:[2,3,0,1] row_mask:0xf bank_mask:0xf bound_ctrl:1
	v_pk_mul_f32 v[26:27], v[6:7], v[26:27]
	v_mov_b32_e32 v20, v23
	v_add_f32_dpp v16, v16, v16 row_half_mirror row_mask:0xf bank_mask:0xf bound_ctrl:1
	s_nop 1
	v_add_f32_dpp v16, v16, v16 row_mirror row_mask:0xf bank_mask:0xf bound_ctrl:1
	s_nop 0
	v_readlane_b32 s43, v16, 16
	v_readlane_b32 s52, v16, 48
	v_readlane_b32 s64, v16, 0
	v_readlane_b32 s65, v16, 32
	v_mov_b32_e32 v34, s43
	v_mov_b32_e32 v35, s52
	v_pk_add_f32 v[34:35], s[64:65], v[34:35]
	s_nop 0
	v_add_f32_e32 v16, v34, v35
	v_add_f32_e32 v16, 0x358637bd, v16
	v_mul_f32_e32 v18, 0x4b800000, v16
	v_cmp_gt_f32_e32 vcc, s68, v16
	s_nop 1
	v_cndmask_b32_e32 v16, v16, v18, vcc
	v_rsq_f32_e32 v16, v16
	s_nop 0
	v_mul_f32_e32 v5, 0x45800000, v16
	v_cndmask_b32_e32 v5, v16, v5, vcc
	v_add_f32_e32 v16, v30, v31
	v_add_f32_e32 v16, v16, v32
	v_add_f32_e32 v16, v16, v33
	v_mul_f32_e32 v18, 0xbfb8aa3b, v16
	v_exp_f32_e32 v18, v18
	v_mul_f32_e32 v5, 0x3e000000, v5
	v_mul_f32_e32 v5, v14, v5
	v_or_b32_e32 v30, 0x180, v0
	v_add_f32_e32 v14, 1.0, v18
	v_rcp_f32_e32 v14, v14
	v_ashrrev_i32_e32 v31, 31, v30
	v_cvt_pk_bf16_f32 v5, v5, s0
	v_lshl_add_u64 v[30:31], v[30:31], 1, s[6:7]
	v_mul_f32_e32 v10, v16, v14
	v_mul_f32_e32 v12, v10, v10
	global_store_short v[30:31], v5, off
	v_pk_mul_f32 v[30:31], v[8:9], v[24:25]
	v_mov_b32_dpp v12, v12 quad_perm:[1,0,3,2] row_mask:0xf bank_mask:0xf bound_ctrl:1
	v_fmac_f32_e32 v12, v10, v10
	ds_write_b16 v44, v5
	v_pk_mul_f32 v[24:25], v[6:7], v[24:25]
	v_add_f32_dpp v12, v12, v12 quad_perm:[2,3,0,1] row_mask:0xf bank_mask:0xf bound_ctrl:1
	s_nop 1
	v_add_f32_dpp v12, v12, v12 row_half_mirror row_mask:0xf bank_mask:0xf bound_ctrl:1
	s_nop 1
	v_add_f32_dpp v12, v12, v12 row_mirror row_mask:0xf bank_mask:0xf bound_ctrl:1
	s_nop 0
	v_readlane_b32 s43, v12, 16
	v_readlane_b32 s52, v12, 48
	v_readlane_b32 s64, v12, 0
	v_readlane_b32 s65, v12, 32
	v_mov_b32_e32 v32, s43
	v_mov_b32_e32 v33, s52
	v_pk_add_f32 v[32:33], s[64:65], v[32:33]
	s_nop 0
	v_add_f32_e32 v12, v32, v33
	v_add_f32_e32 v12, 0x358637bd, v12
	v_mul_f32_e32 v14, 0x4b800000, v12
	v_cmp_gt_f32_e32 vcc, s68, v12
	s_nop 1
	v_cndmask_b32_e32 v12, v12, v14, vcc
	v_add_f32_e32 v14, v28, v29
	v_rsq_f32_e32 v12, v12
	v_add_f32_e32 v14, v14, v30
	v_add_f32_e32 v14, v14, v31
	v_mul_f32_e32 v16, 0xbfb8aa3b, v14
	v_exp_f32_e32 v16, v16
	v_mul_f32_e32 v5, 0x45800000, v12
	v_cndmask_b32_e32 v5, v12, v5, vcc
	v_mul_f32_e32 v5, 0x3e000000, v5
	v_mul_f32_e32 v5, v10, v5
	v_add_f32_e32 v10, 1.0, v16
	v_rcp_f32_e32 v10, v10
	v_or_b32_e32 v28, 0x1c0, v0
	v_ashrrev_i32_e32 v29, 31, v28
	v_cvt_pk_bf16_f32 v5, v5, s0
	v_mul_f32_e32 v10, v14, v10
	v_mul_f32_e32 v12, v10, v10
	v_lshl_add_u64 v[28:29], v[28:29], 1, s[6:7]
	global_store_short v[28:29], v5, off
	v_mov_b32_dpp v12, v12 quad_perm:[1,0,3,2] row_mask:0xf bank_mask:0xf bound_ctrl:1
	v_fmac_f32_e32 v12, v10, v10
	v_pk_mul_f32 v[28:29], v[8:9], v[22:23]
	ds_write_b16 v44, v5 offset:144
	v_add_f32_dpp v12, v12, v12 quad_perm:[2,3,0,1] row_mask:0xf bank_mask:0xf bound_ctrl:1
	v_pk_mul_f32 v[22:23], v[6:7], v[22:23]
	s_nop 0
	v_add_f32_dpp v12, v12, v12 row_half_mirror row_mask:0xf bank_mask:0xf bound_ctrl:1
	s_nop 1
	v_add_f32_dpp v12, v12, v12 row_mirror row_mask:0xf bank_mask:0xf bound_ctrl:1
	s_nop 0
	v_readlane_b32 s43, v12, 16
	v_readlane_b32 s52, v12, 48
	v_readlane_b32 s64, v12, 0
	v_readlane_b32 s65, v12, 32
	v_mov_b32_e32 v30, s43
	v_mov_b32_e32 v31, s52
	v_pk_add_f32 v[30:31], s[64:65], v[30:31]
	s_nop 0
	v_add_f32_e32 v12, v30, v31
	v_add_f32_e32 v12, 0x358637bd, v12
	v_mul_f32_e32 v14, 0x4b800000, v12
	v_cmp_gt_f32_e32 vcc, s68, v12
	s_nop 1
	v_cndmask_b32_e32 v12, v12, v14, vcc
	v_add_f32_e32 v14, v26, v27
	v_rsq_f32_e32 v12, v12
	v_add_f32_e32 v14, v14, v28
	v_add_f32_e32 v14, v14, v29
	v_mul_f32_e32 v16, 0xbfb8aa3b, v14
	v_exp_f32_e32 v16, v16
	v_mul_f32_e32 v5, 0x45800000, v12
	v_cndmask_b32_e32 v5, v12, v5, vcc
	v_mul_f32_e32 v5, 0x3e000000, v5
	v_mul_f32_e32 v5, v10, v5
	v_add_f32_e32 v10, 1.0, v16
	v_rcp_f32_e32 v10, v10
	v_or_b32_e32 v26, 0x200, v0
	v_ashrrev_i32_e32 v27, 31, v26
	v_cvt_pk_bf16_f32 v5, v5, s0
	v_mul_f32_e32 v10, v14, v10
	v_mul_f32_e32 v12, v10, v10
	v_lshl_add_u64 v[26:27], v[26:27], 1, s[6:7]
	global_store_short v[26:27], v5, off
	v_mov_b32_dpp v12, v12 quad_perm:[1,0,3,2] row_mask:0xf bank_mask:0xf bound_ctrl:1
	v_fmac_f32_e32 v12, v10, v10
	v_pk_mul_f32 v[26:27], v[8:9], v[20:21]
	ds_write_b16 v44, v5 offset:288
	v_add_f32_dpp v12, v12, v12 quad_perm:[2,3,0,1] row_mask:0xf bank_mask:0xf bound_ctrl:1
	s_nop 1
	v_add_f32_dpp v12, v12, v12 row_half_mirror row_mask:0xf bank_mask:0xf bound_ctrl:1
	s_nop 1
	v_add_f32_dpp v12, v12, v12 row_mirror row_mask:0xf bank_mask:0xf bound_ctrl:1
	s_nop 0
	v_readlane_b32 s43, v12, 16
	v_readlane_b32 s52, v12, 48
	v_readlane_b32 s64, v12, 0
	v_readlane_b32 s65, v12, 32
	v_mov_b32_e32 v28, s43
	v_mov_b32_e32 v29, s52
	v_pk_add_f32 v[28:29], s[64:65], v[28:29]
	s_nop 0
	v_add_f32_e32 v12, v28, v29
	v_add_f32_e32 v12, 0x358637bd, v12
	v_mul_f32_e32 v14, 0x4b800000, v12
	v_cmp_gt_f32_e32 vcc, s68, v12
	s_nop 1
	v_cndmask_b32_e32 v12, v12, v14, vcc
	v_add_f32_e32 v14, v24, v25
	v_rsq_f32_e32 v12, v12
	v_add_f32_e32 v14, v14, v26
	v_add_f32_e32 v14, v14, v27
	v_mul_f32_e32 v16, 0xbfb8aa3b, v14
	v_exp_f32_e32 v16, v16
	v_mul_f32_e32 v5, 0x45800000, v12
	v_cndmask_b32_e32 v5, v12, v5, vcc
	v_mul_f32_e32 v5, 0x3e000000, v5
	v_mul_f32_e32 v5, v10, v5
	v_add_f32_e32 v10, 1.0, v16
	v_rcp_f32_e32 v10, v10
	v_or_b32_e32 v24, 0x240, v0
	v_ashrrev_i32_e32 v25, 31, v24
	v_cvt_pk_bf16_f32 v5, v5, s0
	v_mul_f32_e32 v10, v14, v10
	v_mul_f32_e32 v12, v10, v10
	v_lshl_add_u64 v[24:25], v[24:25], 1, s[6:7]
	global_store_short v[24:25], v5, off
	v_mov_b32_dpp v12, v12 quad_perm:[1,0,3,2] row_mask:0xf bank_mask:0xf bound_ctrl:1
	v_fmac_f32_e32 v12, v10, v10
	v_add_f32_e32 v16, v22, v23
	ds_write_b16 v44, v5 offset:432
	v_add_f32_dpp v12, v12, v12 quad_perm:[2,3,0,1] row_mask:0xf bank_mask:0xf bound_ctrl:1
	v_or_b32_e32 v22, 0x280, v0
	v_ashrrev_i32_e32 v23, 31, v22
	v_add_f32_dpp v12, v12, v12 row_half_mirror row_mask:0xf bank_mask:0xf bound_ctrl:1
	v_lshl_add_u64 v[22:23], v[22:23], 1, s[6:7]
	s_nop 0
	v_add_f32_dpp v12, v12, v12 row_mirror row_mask:0xf bank_mask:0xf bound_ctrl:1
	s_nop 0
	v_readlane_b32 s43, v12, 16
	v_readlane_b32 s52, v12, 48
	v_readlane_b32 s64, v12, 0
	v_readlane_b32 s65, v12, 32
	v_mov_b32_e32 v26, s43
	v_mov_b32_e32 v27, s52
	v_pk_add_f32 v[26:27], s[64:65], v[26:27]
	s_nop 0
	v_add_f32_e32 v12, v26, v27
	v_add_f32_e32 v12, 0x358637bd, v12
	v_mul_f32_e32 v14, 0x4b800000, v12
	v_cmp_gt_f32_e32 vcc, s68, v12
	s_nop 1
	v_cndmask_b32_e32 v12, v12, v14, vcc
	v_rsq_f32_e32 v14, v12
	v_mov_b32_e32 v12, v21
	v_pk_mul_f32 v[24:25], v[8:9], v[12:13]
	v_pk_mul_f32 v[20:21], v[6:7], v[20:21]
	v_add_f32_e32 v16, v16, v24
	v_add_f32_e32 v16, v16, v25
	v_mul_f32_e32 v18, 0xbfb8aa3b, v16
	v_exp_f32_e32 v18, v18
	v_mul_f32_e32 v5, 0x45800000, v14
	v_cndmask_b32_e32 v5, v14, v5, vcc
	v_mul_f32_e32 v5, 0x3e000000, v5
	v_mul_f32_e32 v5, v10, v5
	v_add_f32_e32 v10, 1.0, v18
	v_rcp_f32_e32 v10, v10
	v_cvt_pk_bf16_f32 v5, v5, s0
	global_store_short v[22:23], v5, off
	v_add_f32_e32 v18, v20, v21
	v_mul_f32_e32 v14, v16, v10
	v_mul_f32_e32 v10, v14, v14
	ds_write_b16 v44, v5 offset:576
	s_nop 0
	v_mov_b32_dpp v10, v10 quad_perm:[1,0,3,2] row_mask:0xf bank_mask:0xf bound_ctrl:1
	v_fmac_f32_e32 v10, v14, v14
	s_nop 1
	v_add_f32_dpp v10, v10, v10 quad_perm:[2,3,0,1] row_mask:0xf bank_mask:0xf bound_ctrl:1
	s_nop 1
	v_add_f32_dpp v10, v10, v10 row_half_mirror row_mask:0xf bank_mask:0xf bound_ctrl:1
	s_nop 1
	v_add_f32_dpp v10, v10, v10 row_mirror row_mask:0xf bank_mask:0xf bound_ctrl:1
	s_nop 0
	v_readlane_b32 s43, v10, 16
	v_readlane_b32 s52, v10, 48
	v_readlane_b32 s64, v10, 0
	v_readlane_b32 s65, v10, 32
	v_mov_b32_e32 v24, s43
	v_mov_b32_e32 v25, s52
	v_pk_add_f32 v[24:25], s[64:65], v[24:25]
	s_nop 0
	v_add_f32_e32 v10, v24, v25
	v_add_f32_e32 v10, 0x358637bd, v10
	v_mul_f32_e32 v16, 0x4b800000, v10
	v_cmp_gt_f32_e32 vcc, s68, v10
	s_nop 1
	v_cndmask_b32_e32 v10, v10, v16, vcc
	v_rsq_f32_e32 v16, v10
	v_mov_b32_e32 v10, v13
	v_pk_mul_f32 v[22:23], v[8:9], v[10:11]
	v_pk_mul_f32 v[12:13], v[6:7], v[12:13]
	v_add_f32_e32 v18, v18, v22
	v_add_f32_e32 v18, v18, v23
	v_mul_f32_e32 v20, 0xbfb8aa3b, v18
	v_exp_f32_e32 v20, v20
	v_mul_f32_e32 v5, 0x45800000, v16
	v_cndmask_b32_e32 v5, v16, v5, vcc
	v_mul_f32_e32 v5, 0x3e000000, v5
	v_mul_f32_e32 v5, v14, v5
	v_add_f32_e32 v14, 1.0, v20
	v_rcp_f32_e32 v14, v14
	v_or_b32_e32 v20, 0x2c0, v0
	v_ashrrev_i32_e32 v21, 31, v20
	v_cvt_pk_bf16_f32 v5, v5, s0
	v_mul_f32_e32 v14, v18, v14
	v_mul_f32_e32 v16, v14, v14
	v_lshl_add_u64 v[20:21], v[20:21], 1, s[6:7]
	global_store_short v[20:21], v5, off
	v_mov_b32_dpp v16, v16 quad_perm:[1,0,3,2] row_mask:0xf bank_mask:0xf bound_ctrl:1
	v_fmac_f32_e32 v16, v14, v14
	v_add_f32_e32 v12, v12, v13
	ds_write_b16 v44, v5 offset:720
	v_add_f32_dpp v16, v16, v16 quad_perm:[2,3,0,1] row_mask:0xf bank_mask:0xf bound_ctrl:1
	s_nop 1
	v_add_f32_dpp v16, v16, v16 row_half_mirror row_mask:0xf bank_mask:0xf bound_ctrl:1
	s_nop 1
	v_add_f32_dpp v16, v16, v16 row_mirror row_mask:0xf bank_mask:0xf bound_ctrl:1
	s_nop 0
	v_readlane_b32 s43, v16, 16
	v_readlane_b32 s52, v16, 48
	v_readlane_b32 s64, v16, 0
	v_readlane_b32 s65, v16, 32
	v_mov_b32_e32 v22, s43
	v_mov_b32_e32 v23, s52
	v_pk_add_f32 v[22:23], s[64:65], v[22:23]
	s_nop 0
	v_add_f32_e32 v16, v22, v23
	v_add_f32_e32 v16, 0x358637bd, v16
	v_mul_f32_e32 v18, 0x4b800000, v16
	v_cmp_gt_f32_e32 vcc, s68, v16
	s_nop 1
	v_cndmask_b32_e32 v16, v16, v18, vcc
	v_rsq_f32_e32 v18, v16
	v_mov_b32_e32 v16, v11
	v_pk_mul_f32 v[20:21], v[8:9], v[16:17]
	v_pk_mul_f32 v[10:11], v[6:7], v[10:11]
	v_add_f32_e32 v12, v12, v20
	v_add_f32_e32 v13, v12, v21
	v_mul_f32_e32 v12, 0xbfb8aa3b, v13
	v_exp_f32_e32 v12, v12
	v_mul_f32_e32 v5, 0x45800000, v18
	v_cndmask_b32_e32 v5, v18, v5, vcc
	v_mul_f32_e32 v5, 0x3e000000, v5
	v_add_f32_e32 v12, 1.0, v12
	v_mul_f32_e32 v5, v14, v5
	v_rcp_f32_e32 v14, v12
	v_or_b32_e32 v12, 0x300, v0
	v_cvt_pk_bf16_f32 v5, v5, s0
	v_add_f32_e32 v10, v10, v11
	v_mul_f32_e32 v18, v13, v14
	v_mul_f32_e32 v13, v18, v18
	ds_write_b16 v44, v5 offset:864
	v_pk_mul_f32 v[6:7], v[6:7], v[16:17]
	v_mov_b32_dpp v13, v13 quad_perm:[1,0,3,2] row_mask:0xf bank_mask:0xf bound_ctrl:1
	v_fmac_f32_e32 v13, v18, v18
	v_add_f32_e32 v6, v6, v7
	s_nop 0
	v_add_f32_dpp v13, v13, v13 quad_perm:[2,3,0,1] row_mask:0xf bank_mask:0xf bound_ctrl:1
	s_nop 1
	v_add_f32_dpp v13, v13, v13 row_half_mirror row_mask:0xf bank_mask:0xf bound_ctrl:1
	s_nop 1
	v_add_f32_dpp v13, v13, v13 row_mirror row_mask:0xf bank_mask:0xf bound_ctrl:1
	s_nop 0
	v_readlane_b32 s43, v13, 16
	v_readlane_b32 s52, v13, 48
	v_readlane_b32 s64, v13, 0
	v_readlane_b32 s65, v13, 32
	v_mov_b32_e32 v20, s43
	v_mov_b32_e32 v21, s52
	v_pk_add_f32 v[20:21], s[64:65], v[20:21]
	s_mov_b64 s[64:65], 0x400
	v_add_f32_e32 v13, v20, v21
	v_add_f32_e32 v13, 0x358637bd, v13
	v_mul_f32_e32 v14, 0x4b800000, v13
	v_cmp_gt_f32_e32 vcc, s68, v13
	s_nop 1
	v_cndmask_b32_e32 v13, v13, v14, vcc
	v_rsq_f32_e32 v20, v13
	v_ashrrev_i32_e32 v13, 31, v12
	v_lshl_add_u64 v[12:13], v[12:13], 1, s[6:7]
	v_mov_b32_e32 v14, v17
	global_store_short v[12:13], v5, off
	v_pk_mul_f32 v[12:13], v[8:9], v[14:15]
	v_mul_f32_e32 v5, 0x45800000, v20
	v_add_f32_e32 v10, v10, v12
	v_add_f32_e32 v14, v10, v13
	v_mul_f32_e32 v10, 0xbfb8aa3b, v14
	v_exp_f32_e32 v10, v10
	v_cndmask_b32_e32 v5, v20, v5, vcc
	v_add_co_u32_e32 v20, vcc, 0x1000, v2
	v_mul_f32_e32 v5, 0x3e000000, v5
	s_nop 0
	v_addc_co_u32_e32 v21, vcc, 0, v3, vcc
	v_lshl_add_u64 v[12:13], v[2:3], 0, s[64:65]
	v_add_co_u32_e32 v22, vcc, 0x2000, v2
	v_mul_f32_e32 v5, v18, v5
	v_add_f32_e32 v18, 1.0, v10
	v_addc_co_u32_e32 v23, vcc, 0, v3, vcc
	global_load_dword v10, v[2:3], off offset:1024
	global_load_dword v11, v[12:13], off offset:3072
	s_nop 0
	global_load_dword v12, v[20:21], off offset:3072
	global_load_dword v13, v[22:23], off offset:2048
	v_rcp_f32_e32 v18, v18
	v_or_b32_e32 v20, 0x340, v0
	v_cvt_pk_bf16_f32 v5, v5, s0
	ds_write_b16 v44, v5 offset:1008
	v_mul_f32_e32 v14, v14, v18
	v_mul_f32_e32 v18, v14, v14
	s_nop 1
	v_mov_b32_dpp v18, v18 quad_perm:[1,0,3,2] row_mask:0xf bank_mask:0xf bound_ctrl:1
	v_fmac_f32_e32 v18, v14, v14
	s_nop 1
	v_add_f32_dpp v18, v18, v18 quad_perm:[2,3,0,1] row_mask:0xf bank_mask:0xf bound_ctrl:1
	s_nop 1
	v_add_f32_dpp v18, v18, v18 row_half_mirror row_mask:0xf bank_mask:0xf bound_ctrl:1
	s_nop 1
	v_add_f32_dpp v18, v18, v18 row_mirror row_mask:0xf bank_mask:0xf bound_ctrl:1
	s_nop 0
	v_readlane_b32 s43, v18, 16
	v_readlane_b32 s52, v18, 48
	v_readlane_b32 s64, v18, 0
	v_readlane_b32 s65, v18, 32
	v_mov_b32_e32 v22, s43
	v_mov_b32_e32 v23, s52
	v_pk_add_f32 v[22:23], s[64:65], v[22:23]
	s_nop 0
	v_add_f32_e32 v18, v22, v23
	v_add_f32_e32 v18, 0x358637bd, v18
	v_mul_f32_e32 v21, 0x4b800000, v18
	v_cmp_gt_f32_e32 vcc, s68, v18
	s_nop 1
	v_cndmask_b32_e32 v18, v18, v21, vcc
	v_rsq_f32_e32 v22, v18
	v_mov_b32_e32 v18, v15
	v_pk_mul_f32 v[8:9], v[8:9], v[18:19]
	v_ashrrev_i32_e32 v21, 31, v20
	v_add_f32_e32 v6, v6, v8
	v_add_f32_e32 v7, v6, v9
	v_mul_f32_e32 v6, 0xbfb8aa3b, v7
	v_exp_f32_e32 v6, v6
	v_lshl_add_u64 v[20:21], v[20:21], 1, s[6:7]
	global_store_short v[20:21], v5, off
	v_mul_f32_e32 v5, 0x45800000, v22
	v_add_f32_e32 v6, 1.0, v6
	v_rcp_f32_e32 v8, v6
	v_cndmask_b32_e32 v5, v22, v5, vcc
	v_mul_f32_e32 v5, 0x3e000000, v5
	v_mul_f32_e32 v5, v14, v5
	v_mul_f32_e32 v14, v7, v8
	v_mul_f32_e32 v7, v14, v14
	v_or_b32_e32 v6, 0x380, v0
	v_cvt_pk_bf16_f32 v5, v5, s0
	v_mov_b32_dpp v7, v7 quad_perm:[1,0,3,2] row_mask:0xf bank_mask:0xf bound_ctrl:1
	v_fmac_f32_e32 v7, v14, v14
	ds_write_b16 v44, v5 offset:1152
	s_nop 0
	v_add_f32_dpp v7, v7, v7 quad_perm:[2,3,0,1] row_mask:0xf bank_mask:0xf bound_ctrl:1
	s_nop 1
	v_add_f32_dpp v7, v7, v7 row_half_mirror row_mask:0xf bank_mask:0xf bound_ctrl:1
	s_nop 1
	v_add_f32_dpp v7, v7, v7 row_mirror row_mask:0xf bank_mask:0xf bound_ctrl:1
	s_nop 0
	v_readlane_b32 s43, v7, 16
	v_readlane_b32 s52, v7, 48
	v_readlane_b32 s64, v7, 0
	v_readlane_b32 s65, v7, 32
	v_mov_b32_e32 v8, s43
	v_mov_b32_e32 v9, s52
	v_pk_add_f32 v[8:9], s[64:65], v[8:9]
	s_nop 0
	v_add_f32_e32 v7, v8, v9
	v_add_f32_e32 v7, 0x358637bd, v7
	v_mul_f32_e32 v8, 0x4b800000, v7
	v_cmp_gt_f32_e32 vcc, s68, v7
	s_nop 1
	v_cndmask_b32_e32 v7, v7, v8, vcc
	v_rsq_f32_e32 v8, v7
	v_ashrrev_i32_e32 v7, 31, v6
	v_lshl_add_u64 v[6:7], v[6:7], 1, s[6:7]
	global_store_short v[6:7], v5, off
	v_mul_f32_e32 v5, 0x45800000, v8
	v_cndmask_b32_e32 v5, v8, v5, vcc
	v_mul_f32_e32 v5, 0x3e000000, v5
	v_or_b32_e32 v6, 0x3c0, v0
	v_mul_f32_e32 v5, v14, v5
	v_ashrrev_i32_e32 v7, 31, v6
	v_or_b32_e32 v0, 0x100, v50
	v_cvt_pk_bf16_f32 v5, v5, s0
	v_lshl_add_u64 v[6:7], v[6:7], 1, s[6:7]
	v_lshlrev_b32_e32 v0, 1, v0
	ds_write_b16 v44, v5 offset:1296
	global_store_short v[6:7], v5, off
	s_waitcnt vmcnt(39)
	s_and_saveexec_b64 s[6:7], s[10:11]
	s_cbranch_execz .LBB0_609
	v_mov_b32_e32 v4, v134
.LBB0_609:
	s_or_b64 exec, exec, s[6:7]
	v_mov_b32_e32 v40, 0
	v_mov_b32_e32 v5, 0
	s_and_saveexec_b64 s[6:7], s[18:19]
	s_cbranch_execz .LBB0_611
	v_mov_b32_e32 v5, v135
.LBB0_611:
	s_or_b64 exec, exec, s[6:7]
	s_and_saveexec_b64 s[6:7], s[20:21]
	s_cbranch_execz .LBB0_613
	v_mov_b32_e32 v40, v136
.LBB0_613:
	s_or_b64 exec, exec, s[6:7]
	v_mov_b32_e32 v39, 0
	v_mov_b32_e32 v41, 0
	s_and_saveexec_b64 s[6:7], s[22:23]
	s_cbranch_execz .LBB0_615
	v_mov_b32_e32 v41, v137
.LBB0_615:
	s_or_b64 exec, exec, s[6:7]
	s_and_saveexec_b64 s[6:7], s[24:25]
	s_cbranch_execz .LBB0_617
	v_mov_b32_e32 v39, v138
.LBB0_617:
	s_or_b64 exec, exec, s[6:7]
	v_mov_b32_e32 v35, 0
	v_mov_b32_e32 v37, 0
	s_and_saveexec_b64 s[6:7], s[26:27]
	s_cbranch_execz .LBB0_619
	v_mov_b32_e32 v37, v139
.LBB0_619:
	s_or_b64 exec, exec, s[6:7]
	s_and_saveexec_b64 s[6:7], s[28:29]
	s_cbranch_execz .LBB0_621
	v_mov_b32_e32 v35, v140
.LBB0_621:
	s_or_b64 exec, exec, s[6:7]
	v_mov_b32_e32 v31, 0
	v_mov_b32_e32 v33, 0
	s_and_saveexec_b64 s[6:7], s[30:31]
	s_cbranch_execz .LBB0_623
	v_mov_b32_e32 v33, v141
.LBB0_623:
	s_or_b64 exec, exec, s[6:7]
	s_and_saveexec_b64 s[6:7], s[34:35]
	s_cbranch_execz .LBB0_625
	v_mov_b32_e32 v31, v142
.LBB0_625:
	s_or_b64 exec, exec, s[6:7]
	v_mov_b32_e32 v27, 0
	v_mov_b32_e32 v29, 0
	s_and_saveexec_b64 s[6:7], s[36:37]
	s_cbranch_execz .LBB0_627
	v_mov_b32_e32 v29, v143
.LBB0_627:
	s_or_b64 exec, exec, s[6:7]
	s_and_saveexec_b64 s[6:7], s[38:39]
	s_cbranch_execz .LBB0_629
	v_mov_b32_e32 v27, v144
.LBB0_629:
	s_or_b64 exec, exec, s[6:7]
	v_mov_b32_e32 v23, 0
	v_mov_b32_e32 v25, 0
	s_and_saveexec_b64 s[6:7], s[44:45]
	s_cbranch_execz .LBB0_631
	v_mov_b32_e32 v25, v145
.LBB0_631:
	s_or_b64 exec, exec, s[6:7]
	s_and_saveexec_b64 s[6:7], s[48:49]
	s_cbranch_execz .LBB0_633
	v_mov_b32_e32 v23, v146
.LBB0_633:
	s_or_b64 exec, exec, s[6:7]
	v_mov_b32_e32 v19, 0
	v_mov_b32_e32 v21, 0
	s_and_saveexec_b64 s[6:7], s[50:51]
	s_cbranch_execz .LBB0_635
	v_mov_b32_e32 v21, v147
.LBB0_635:
	s_or_b64 exec, exec, s[6:7]
	s_and_saveexec_b64 s[6:7], s[56:57]
	s_cbranch_execz .LBB0_637
	v_mov_b32_e32 v19, v148
.LBB0_637:
	s_or_b64 exec, exec, s[6:7]
	v_mov_b32_e32 v7, 0
	v_mov_b32_e32 v9, 0
	s_and_saveexec_b64 s[6:7], s[58:59]
	s_cbranch_execz .LBB0_639
	v_mov_b32_e32 v9, v149
.LBB0_639:
	s_or_b64 exec, exec, s[6:7]
	s_and_saveexec_b64 s[6:7], s[60:61]
	s_cbranch_execz .LBB0_641
	v_mov_b32_e32 v7, v150
.LBB0_641:
	s_or_b64 exec, exec, s[6:7]
	v_mov_b32_e32 v15, 0
	v_mov_b32_e32 v17, 0
	s_and_saveexec_b64 s[6:7], s[70:71]
	s_cbranch_execz .LBB0_643
	v_mov_b32_e32 v17, v151
.LBB0_643:
	s_or_b64 exec, exec, s[6:7]
	s_and_saveexec_b64 s[6:7], s[84:85]
	s_cbranch_execz .LBB0_645
	v_mov_b32_e32 v15, v152
.LBB0_645:
	s_or_b64 exec, exec, s[6:7]
	v_lshlrev_b32_e32 v4, 16, v4
	v_lshlrev_b32_e32 v5, 16, v5
	v_lshlrev_b32_e32 v40, 16, v40
	v_lshlrev_b32_e32 v41, 16, v41
	v_lshlrev_b32_e32 v39, 16, v39
	v_lshlrev_b32_e32 v37, 16, v37
	v_lshlrev_b32_e32 v35, 16, v35
	v_lshlrev_b32_e32 v33, 16, v33
	v_lshlrev_b32_e32 v31, 16, v31
	v_lshlrev_b32_e32 v29, 16, v29
	v_lshlrev_b32_e32 v27, 16, v27
	v_lshlrev_b32_e32 v25, 16, v25
	v_lshlrev_b32_e32 v23, 16, v23
	v_lshlrev_b32_e32 v21, 16, v21
	v_lshlrev_b32_e32 v19, 16, v19
	v_lshlrev_b32_e32 v9, 16, v9
	v_lshlrev_b32_e32 v7, 16, v7
	v_lshlrev_b32_e32 v17, 16, v17
	v_lshlrev_b32_e32 v15, 16, v15
	s_waitcnt vmcnt(5)
	v_pk_mul_f32 v[72:73], v[10:11], v[4:5]
	s_waitcnt vmcnt(3)
	v_pk_mul_f32 v[70:71], v[12:13], v[40:41]
	v_add_f32_e32 v0, v72, v73
	v_add_f32_e32 v0, v0, v70
	v_add_f32_e32 v0, v0, v71
	v_mul_f32_e32 v4, 0xbfb8aa3b, v0
	v_exp_f32_e32 v4, v4
	v_mov_b32_e32 v38, v41
	v_mov_b32_e32 v36, v39
	v_mov_b32_e32 v34, v37
	v_add_f32_e32 v4, 1.0, v4
	v_rcp_f32_e32 v4, v4
	v_mov_b32_e32 v32, v35
	v_mov_b32_e32 v30, v33
	v_mov_b32_e32 v28, v31
	v_mul_f32_e32 v0, v0, v4
	v_mul_f32_e32 v4, v0, v0
	v_mov_b32_e32 v26, v29
	v_mov_b32_e32 v24, v27
	v_mov_b32_dpp v4, v4 quad_perm:[1,0,3,2] row_mask:0xf bank_mask:0xf bound_ctrl:1
	v_fmac_f32_e32 v4, v0, v0
	v_mov_b32_e32 v22, v25
	v_mov_b32_e32 v20, v23
	v_add_f32_dpp v4, v4, v4 quad_perm:[2,3,0,1] row_mask:0xf bank_mask:0xf bound_ctrl:1
	v_mov_b32_e32 v18, v21
	s_mov_b64 s[64:65], 0x800
	v_add_f32_dpp v4, v4, v4 row_half_mirror row_mask:0xf bank_mask:0xf bound_ctrl:1
	s_nop 1
	v_add_f32_dpp v4, v4, v4 row_mirror row_mask:0xf bank_mask:0xf bound_ctrl:1
	s_nop 0
	v_readlane_b32 s43, v4, 16
	v_readlane_b32 s52, v4, 48
	v_readlane_b32 s6, v4, 0
	v_readlane_b32 s7, v4, 32
	v_mov_b32_e32 v70, s43
	v_mov_b32_e32 v71, s52
	v_pk_add_f32 v[70:71], s[6:7], v[70:71]
	s_nop 0
	v_add_f32_e32 v4, v70, v71
	v_add_f32_e32 v6, 0x358637bd, v4
	v_mov_b32_e32 v4, v5
	v_mov_b32_e32 v5, v40
	v_pk_mul_f32 v[4:5], v[10:11], v[4:5]
	v_pk_mul_f32 v[70:71], v[12:13], v[38:39]
	v_add_f32_e32 v4, v4, v5
	v_add_f32_e32 v4, v4, v70
	v_add_f32_e32 v4, v4, v71
	v_mul_f32_e32 v5, 0xbfb8aa3b, v4
	v_exp_f32_e32 v5, v5
	v_mul_f32_e32 v8, 0x4b800000, v6
	v_cmp_gt_f32_e32 vcc, s68, v6
	v_pk_mul_f32 v[40:41], v[10:11], v[40:41]
	v_add_f32_e32 v5, 1.0, v5
	v_cndmask_b32_e32 v6, v6, v8, vcc
	v_rsq_f32_e32 v6, v6
	v_rcp_f32_e32 v5, v5
	v_add_f32_e32 v14, v40, v41
	v_pk_mul_f32 v[38:39], v[10:11], v[38:39]
	v_mul_f32_e32 v8, 0x45800000, v6
	v_cndmask_b32_e32 v6, v6, v8, vcc
	v_mul_f32_e32 v0, v0, v6
	v_mul_f32_e32 v6, v4, v5
	v_mul_f32_e32 v4, v6, v6
	v_cvt_pk_bf16_f32 v0, v0, s0
	ds_write_b16 v43, v0 offset:9216
	v_mov_b32_dpp v4, v4 quad_perm:[1,0,3,2] row_mask:0xf bank_mask:0xf bound_ctrl:1
	v_fmac_f32_e32 v4, v6, v6
	v_add_f32_e32 v16, v38, v39
	s_nop 0
	v_add_f32_dpp v4, v4, v4 quad_perm:[2,3,0,1] row_mask:0xf bank_mask:0xf bound_ctrl:1
	s_nop 1
	v_add_f32_dpp v4, v4, v4 row_half_mirror row_mask:0xf bank_mask:0xf bound_ctrl:1
	s_nop 1
	v_add_f32_dpp v4, v4, v4 row_mirror row_mask:0xf bank_mask:0xf bound_ctrl:1
	s_nop 0
	v_readlane_b32 s43, v4, 16
	v_readlane_b32 s52, v4, 48
	v_readlane_b32 s6, v4, 0
	v_readlane_b32 s7, v4, 32
	v_mov_b32_e32 v4, s43
	v_mov_b32_e32 v5, s52
	v_pk_add_f32 v[4:5], s[6:7], v[4:5]
	s_nop 0
	v_add_f32_e32 v4, v4, v5
	v_add_f32_e32 v4, 0x358637bd, v4
	v_mul_f32_e32 v5, 0x4b800000, v4
	v_cmp_gt_f32_e32 vcc, s68, v4
	s_nop 1
	v_cndmask_b32_e32 v4, v4, v5, vcc
	v_rsq_f32_e32 v8, v4
	v_pk_mul_f32 v[4:5], v[12:13], v[36:37]
	v_pk_mul_f32 v[36:37], v[10:11], v[36:37]
	v_add_f32_e32 v4, v14, v4
	v_add_f32_e32 v4, v4, v5
	v_mul_f32_e32 v5, 0xbfb8aa3b, v4
	v_exp_f32_e32 v5, v5
	v_mul_f32_e32 v0, 0x45800000, v8
	v_cndmask_b32_e32 v0, v8, v0, vcc
	v_mul_f32_e32 v0, v6, v0
	v_add_f32_e32 v5, 1.0, v5
	v_rcp_f32_e32 v5, v5
	v_cvt_pk_bf16_f32 v0, v0, s0
	ds_write_b16 v42, v0 offset:9216
	v_mul_f32_e32 v6, v4, v5
	v_mul_f32_e32 v4, v6, v6
	s_nop 1
	v_mov_b32_dpp v4, v4 quad_perm:[1,0,3,2] row_mask:0xf bank_mask:0xf bound_ctrl:1
	v_fmac_f32_e32 v4, v6, v6
	s_nop 1
	v_add_f32_dpp v4, v4, v4 quad_perm:[2,3,0,1] row_mask:0xf bank_mask:0xf bound_ctrl:1
	s_nop 1
	v_add_f32_dpp v4, v4, v4 row_half_mirror row_mask:0xf bank_mask:0xf bound_ctrl:1
	s_nop 1
	v_add_f32_dpp v4, v4, v4 row_mirror row_mask:0xf bank_mask:0xf bound_ctrl:1
	s_nop 0
	v_readlane_b32 s43, v4, 16
	v_readlane_b32 s52, v4, 48
	v_readlane_b32 s6, v4, 0
	v_readlane_b32 s7, v4, 32
	v_mov_b32_e32 v4, s43
	v_mov_b32_e32 v5, s52
	v_pk_add_f32 v[4:5], s[6:7], v[4:5]
	s_nop 0
	v_add_f32_e32 v4, v4, v5
	v_add_f32_e32 v8, 0x358637bd, v4
	v_pk_mul_f32 v[4:5], v[12:13], v[34:35]
	v_mul_f32_e32 v14, 0x4b800000, v8
	v_add_f32_e32 v4, v16, v4
	v_add_f32_e32 v4, v4, v5
	v_mul_f32_e32 v5, 0xbfb8aa3b, v4
	v_exp_f32_e32 v5, v5
	v_cmp_gt_f32_e32 vcc, s68, v8
	v_pk_mul_f32 v[34:35], v[10:11], v[34:35]
	v_add_f32_e32 v0, 1.0, v5
	v_rcp_f32_e32 v0, v0
	v_cndmask_b32_e32 v8, v8, v14, vcc
	v_rsq_f32_e32 v8, v8
	v_add_f32_e32 v14, v36, v37
	v_mul_f32_e32 v0, v4, v0
	v_mul_f32_e32 v4, v0, v0
	v_mul_f32_e32 v5, 0x45800000, v8
	v_cndmask_b32_e32 v5, v8, v5, vcc
	v_mov_b32_dpp v4, v4 quad_perm:[1,0,3,2] row_mask:0xf bank_mask:0xf bound_ctrl:1
	v_fmac_f32_e32 v4, v0, v0
	v_mul_f32_e32 v6, v6, v5
	v_cvt_pk_bf16_f32 v6, v6, s0
	v_add_f32_dpp v4, v4, v4 quad_perm:[2,3,0,1] row_mask:0xf bank_mask:0xf bound_ctrl:1
	ds_write_b16 v42, v6 offset:9360
	v_add_f32_e32 v16, v34, v35
	v_add_f32_dpp v4, v4, v4 row_half_mirror row_mask:0xf bank_mask:0xf bound_ctrl:1
	s_nop 1
	v_add_f32_dpp v4, v4, v4 row_mirror row_mask:0xf bank_mask:0xf bound_ctrl:1
	s_nop 0
	v_readlane_b32 s43, v4, 16
	v_readlane_b32 s52, v4, 48
	v_readlane_b32 s6, v4, 0
	v_readlane_b32 s7, v4, 32
	v_mov_b32_e32 v4, s43
	v_mov_b32_e32 v5, s52
	v_pk_add_f32 v[4:5], s[6:7], v[4:5]
	s_nop 0
	v_add_f32_e32 v4, v4, v5
	v_add_f32_e32 v4, 0x358637bd, v4
	v_mul_f32_e32 v5, 0x4b800000, v4
	v_cmp_gt_f32_e32 vcc, s68, v4
	s_nop 1
	v_cndmask_b32_e32 v4, v4, v5, vcc
	v_rsq_f32_e32 v8, v4
	v_pk_mul_f32 v[4:5], v[12:13], v[32:33]
	v_pk_mul_f32 v[32:33], v[10:11], v[32:33]
	v_add_f32_e32 v4, v14, v4
	v_add_f32_e32 v4, v4, v5
	v_mul_f32_e32 v5, 0xbfb8aa3b, v4
	v_exp_f32_e32 v5, v5
	v_mul_f32_e32 v6, 0x45800000, v8
	v_cndmask_b32_e32 v6, v8, v6, vcc
	v_mul_f32_e32 v0, v0, v6
	v_add_f32_e32 v5, 1.0, v5
	v_rcp_f32_e32 v5, v5
	v_cvt_pk_bf16_f32 v0, v0, s0
	ds_write_b16 v42, v0 offset:9504
	v_mul_f32_e32 v6, v4, v5
	v_mul_f32_e32 v4, v6, v6
	s_nop 1
	v_mov_b32_dpp v4, v4 quad_perm:[1,0,3,2] row_mask:0xf bank_mask:0xf bound_ctrl:1
	v_fmac_f32_e32 v4, v6, v6
	s_nop 1
	v_add_f32_dpp v4, v4, v4 quad_perm:[2,3,0,1] row_mask:0xf bank_mask:0xf bound_ctrl:1
	s_nop 1
	v_add_f32_dpp v4, v4, v4 row_half_mirror row_mask:0xf bank_mask:0xf bound_ctrl:1
	s_nop 1
	v_add_f32_dpp v4, v4, v4 row_mirror row_mask:0xf bank_mask:0xf bound_ctrl:1
	s_nop 0
	v_readlane_b32 s43, v4, 16
	v_readlane_b32 s52, v4, 48
	v_readlane_b32 s6, v4, 0
	v_readlane_b32 s7, v4, 32
	v_mov_b32_e32 v4, s43
	v_mov_b32_e32 v5, s52
	v_pk_add_f32 v[4:5], s[6:7], v[4:5]
	s_nop 0
	v_add_f32_e32 v4, v4, v5
	v_add_f32_e32 v8, 0x358637bd, v4
	v_pk_mul_f32 v[4:5], v[12:13], v[30:31]
	v_mul_f32_e32 v14, 0x4b800000, v8
	v_add_f32_e32 v4, v16, v4
	v_add_f32_e32 v4, v4, v5
	v_mul_f32_e32 v5, 0xbfb8aa3b, v4
	v_exp_f32_e32 v5, v5
	v_cmp_gt_f32_e32 vcc, s68, v8
	v_pk_mul_f32 v[30:31], v[10:11], v[30:31]
	v_add_f32_e32 v0, 1.0, v5
	v_rcp_f32_e32 v0, v0
	v_cndmask_b32_e32 v8, v8, v14, vcc
	v_rsq_f32_e32 v8, v8
	v_add_f32_e32 v14, v32, v33
	v_mul_f32_e32 v0, v4, v0
	v_mul_f32_e32 v4, v0, v0
	v_mul_f32_e32 v5, 0x45800000, v8
	v_cndmask_b32_e32 v5, v8, v5, vcc
	v_mov_b32_dpp v4, v4 quad_perm:[1,0,3,2] row_mask:0xf bank_mask:0xf bound_ctrl:1
	v_fmac_f32_e32 v4, v0, v0
	v_mul_f32_e32 v6, v6, v5
	v_cvt_pk_bf16_f32 v6, v6, s0
	v_add_f32_dpp v4, v4, v4 quad_perm:[2,3,0,1] row_mask:0xf bank_mask:0xf bound_ctrl:1
	ds_write_b16 v42, v6 offset:9648
	v_add_f32_e32 v16, v30, v31
	v_add_f32_dpp v4, v4, v4 row_half_mirror row_mask:0xf bank_mask:0xf bound_ctrl:1
	s_nop 1
	v_add_f32_dpp v4, v4, v4 row_mirror row_mask:0xf bank_mask:0xf bound_ctrl:1
	s_nop 0
	v_readlane_b32 s43, v4, 16
	v_readlane_b32 s52, v4, 48
	v_readlane_b32 s6, v4, 0
	v_readlane_b32 s7, v4, 32
	v_mov_b32_e32 v4, s43
	v_mov_b32_e32 v5, s52
	v_pk_add_f32 v[4:5], s[6:7], v[4:5]
	s_nop 0
	v_add_f32_e32 v4, v4, v5
	v_add_f32_e32 v4, 0x358637bd, v4
	v_mul_f32_e32 v5, 0x4b800000, v4
	v_cmp_gt_f32_e32 vcc, s68, v4
	s_nop 1
	v_cndmask_b32_e32 v4, v4, v5, vcc
	v_rsq_f32_e32 v8, v4
	v_pk_mul_f32 v[4:5], v[12:13], v[28:29]
	v_pk_mul_f32 v[28:29], v[10:11], v[28:29]
	v_add_f32_e32 v4, v14, v4
	v_add_f32_e32 v4, v4, v5
	v_mul_f32_e32 v5, 0xbfb8aa3b, v4
	v_exp_f32_e32 v5, v5
	v_mul_f32_e32 v6, 0x45800000, v8
	v_cndmask_b32_e32 v6, v8, v6, vcc
	v_mul_f32_e32 v0, v0, v6
	v_add_f32_e32 v5, 1.0, v5
	v_rcp_f32_e32 v5, v5
	v_cvt_pk_bf16_f32 v0, v0, s0
	ds_write_b16 v42, v0 offset:9792
	v_mul_f32_e32 v6, v4, v5
	v_mul_f32_e32 v4, v6, v6
	s_nop 1
	v_mov_b32_dpp v4, v4 quad_perm:[1,0,3,2] row_mask:0xf bank_mask:0xf bound_ctrl:1
	v_fmac_f32_e32 v4, v6, v6
	s_nop 1
	v_add_f32_dpp v4, v4, v4 quad_perm:[2,3,0,1] row_mask:0xf bank_mask:0xf bound_ctrl:1
	s_nop 1
	v_add_f32_dpp v4, v4, v4 row_half_mirror row_mask:0xf bank_mask:0xf bound_ctrl:1
	s_nop 1
	v_add_f32_dpp v4, v4, v4 row_mirror row_mask:0xf bank_mask:0xf bound_ctrl:1
	s_nop 0
	v_readlane_b32 s43, v4, 16
	v_readlane_b32 s52, v4, 48
	v_readlane_b32 s6, v4, 0
	v_readlane_b32 s7, v4, 32
	v_mov_b32_e32 v4, s43
	v_mov_b32_e32 v5, s52
	v_pk_add_f32 v[4:5], s[6:7], v[4:5]
	s_nop 0
	v_add_f32_e32 v4, v4, v5
	v_add_f32_e32 v8, 0x358637bd, v4
	v_pk_mul_f32 v[4:5], v[12:13], v[26:27]
	v_mul_f32_e32 v14, 0x4b800000, v8
	v_add_f32_e32 v4, v16, v4
	v_add_f32_e32 v4, v4, v5
	v_mul_f32_e32 v5, 0xbfb8aa3b, v4
	v_exp_f32_e32 v5, v5
	v_cmp_gt_f32_e32 vcc, s68, v8
	v_pk_mul_f32 v[26:27], v[10:11], v[26:27]
	v_add_f32_e32 v0, 1.0, v5
	v_rcp_f32_e32 v0, v0
	v_cndmask_b32_e32 v8, v8, v14, vcc
	v_rsq_f32_e32 v8, v8
	v_add_f32_e32 v14, v28, v29
	v_mul_f32_e32 v0, v4, v0
	v_mul_f32_e32 v4, v0, v0
	v_mul_f32_e32 v5, 0x45800000, v8
	v_cndmask_b32_e32 v5, v8, v5, vcc
	v_mov_b32_dpp v4, v4 quad_perm:[1,0,3,2] row_mask:0xf bank_mask:0xf bound_ctrl:1
	v_fmac_f32_e32 v4, v0, v0
	v_mul_f32_e32 v6, v6, v5
	v_cvt_pk_bf16_f32 v6, v6, s0
	v_add_f32_dpp v4, v4, v4 quad_perm:[2,3,0,1] row_mask:0xf bank_mask:0xf bound_ctrl:1
	ds_write_b16 v44, v6 offset:9216
	v_add_f32_e32 v16, v26, v27
	v_add_f32_dpp v4, v4, v4 row_half_mirror row_mask:0xf bank_mask:0xf bound_ctrl:1
	s_nop 1
	v_add_f32_dpp v4, v4, v4 row_mirror row_mask:0xf bank_mask:0xf bound_ctrl:1
	s_nop 0
	v_readlane_b32 s43, v4, 16
	v_readlane_b32 s52, v4, 48
	v_readlane_b32 s6, v4, 0
	v_readlane_b32 s7, v4, 32
	v_mov_b32_e32 v4, s43
	v_mov_b32_e32 v5, s52
	v_pk_add_f32 v[4:5], s[6:7], v[4:5]
	s_nop 0
	v_add_f32_e32 v4, v4, v5
	v_add_f32_e32 v4, 0x358637bd, v4
	v_mul_f32_e32 v5, 0x4b800000, v4
	v_cmp_gt_f32_e32 vcc, s68, v4
	s_nop 1
	v_cndmask_b32_e32 v4, v4, v5, vcc
	v_rsq_f32_e32 v8, v4
	v_pk_mul_f32 v[4:5], v[12:13], v[24:25]
	v_pk_mul_f32 v[24:25], v[10:11], v[24:25]
	v_add_f32_e32 v4, v14, v4
	v_add_f32_e32 v4, v4, v5
	v_mul_f32_e32 v5, 0xbfb8aa3b, v4
	v_exp_f32_e32 v5, v5
	v_mul_f32_e32 v6, 0x45800000, v8
	v_cndmask_b32_e32 v6, v8, v6, vcc
	v_mul_f32_e32 v0, v0, v6
	v_add_f32_e32 v5, 1.0, v5
	v_rcp_f32_e32 v5, v5
	v_cvt_pk_bf16_f32 v0, v0, s0
	ds_write_b16 v44, v0 offset:9360
	v_mul_f32_e32 v6, v4, v5
	v_mul_f32_e32 v4, v6, v6
	s_nop 1
	v_mov_b32_dpp v4, v4 quad_perm:[1,0,3,2] row_mask:0xf bank_mask:0xf bound_ctrl:1
	v_fmac_f32_e32 v4, v6, v6
	s_nop 1
	v_add_f32_dpp v4, v4, v4 quad_perm:[2,3,0,1] row_mask:0xf bank_mask:0xf bound_ctrl:1
	s_nop 1
	v_add_f32_dpp v4, v4, v4 row_half_mirror row_mask:0xf bank_mask:0xf bound_ctrl:1
	s_nop 1
	v_add_f32_dpp v4, v4, v4 row_mirror row_mask:0xf bank_mask:0xf bound_ctrl:1
	s_nop 0
	v_readlane_b32 s43, v4, 16
	v_readlane_b32 s52, v4, 48
	v_readlane_b32 s6, v4, 0
	v_readlane_b32 s7, v4, 32
	v_mov_b32_e32 v4, s43
	v_mov_b32_e32 v5, s52
	v_pk_add_f32 v[4:5], s[6:7], v[4:5]
	s_nop 0
	v_add_f32_e32 v4, v4, v5
	v_add_f32_e32 v8, 0x358637bd, v4
	v_pk_mul_f32 v[4:5], v[12:13], v[22:23]
	v_mul_f32_e32 v14, 0x4b800000, v8
	v_add_f32_e32 v4, v16, v4
	v_add_f32_e32 v4, v4, v5
	v_mul_f32_e32 v5, 0xbfb8aa3b, v4
	v_exp_f32_e32 v5, v5
	v_cmp_gt_f32_e32 vcc, s68, v8
	v_pk_mul_f32 v[22:23], v[10:11], v[22:23]
	v_add_f32_e32 v0, 1.0, v5
	v_rcp_f32_e32 v0, v0
	v_cndmask_b32_e32 v8, v8, v14, vcc
	v_rsq_f32_e32 v8, v8
	v_add_f32_e32 v14, v24, v25
	v_mul_f32_e32 v0, v4, v0
	v_mul_f32_e32 v4, v0, v0
	v_mul_f32_e32 v5, 0x45800000, v8
	v_cndmask_b32_e32 v5, v8, v5, vcc
	v_mov_b32_dpp v4, v4 quad_perm:[1,0,3,2] row_mask:0xf bank_mask:0xf bound_ctrl:1
	v_fmac_f32_e32 v4, v0, v0
	v_mul_f32_e32 v6, v6, v5
	v_cvt_pk_bf16_f32 v6, v6, s0
	v_add_f32_dpp v4, v4, v4 quad_perm:[2,3,0,1] row_mask:0xf bank_mask:0xf bound_ctrl:1
	ds_write_b16 v44, v6 offset:9504
	v_add_f32_e32 v16, v22, v23
	v_add_f32_dpp v4, v4, v4 row_half_mirror row_mask:0xf bank_mask:0xf bound_ctrl:1
	s_nop 1
	v_add_f32_dpp v4, v4, v4 row_mirror row_mask:0xf bank_mask:0xf bound_ctrl:1
	s_nop 0
	v_readlane_b32 s43, v4, 16
	v_readlane_b32 s52, v4, 48
	v_readlane_b32 s6, v4, 0
	v_readlane_b32 s7, v4, 32
	v_mov_b32_e32 v4, s43
	v_mov_b32_e32 v5, s52
	v_pk_add_f32 v[4:5], s[6:7], v[4:5]
	s_nop 0
	v_add_f32_e32 v4, v4, v5
	v_add_f32_e32 v4, 0x358637bd, v4
	v_mul_f32_e32 v5, 0x4b800000, v4
	v_cmp_gt_f32_e32 vcc, s68, v4
	s_nop 1
	v_cndmask_b32_e32 v4, v4, v5, vcc
	v_rsq_f32_e32 v8, v4
	v_pk_mul_f32 v[4:5], v[12:13], v[20:21]
	v_pk_mul_f32 v[20:21], v[10:11], v[20:21]
	v_add_f32_e32 v4, v14, v4
	v_add_f32_e32 v4, v4, v5
	v_mul_f32_e32 v5, 0xbfb8aa3b, v4
	v_exp_f32_e32 v5, v5
	v_mul_f32_e32 v6, 0x45800000, v8
	v_cndmask_b32_e32 v6, v8, v6, vcc
	v_mul_f32_e32 v0, v0, v6
	v_add_f32_e32 v5, 1.0, v5
	v_rcp_f32_e32 v5, v5
	v_cvt_pk_bf16_f32 v0, v0, s0
	ds_write_b16 v44, v0 offset:9648
	v_mul_f32_e32 v6, v4, v5
	v_mul_f32_e32 v4, v6, v6
	s_nop 1
	v_mov_b32_dpp v4, v4 quad_perm:[1,0,3,2] row_mask:0xf bank_mask:0xf bound_ctrl:1
	v_fmac_f32_e32 v4, v6, v6
	s_nop 1
	v_add_f32_dpp v4, v4, v4 quad_perm:[2,3,0,1] row_mask:0xf bank_mask:0xf bound_ctrl:1
	s_nop 1
	v_add_f32_dpp v4, v4, v4 row_half_mirror row_mask:0xf bank_mask:0xf bound_ctrl:1
	s_nop 1
	v_add_f32_dpp v4, v4, v4 row_mirror row_mask:0xf bank_mask:0xf bound_ctrl:1
	s_nop 0
	v_readlane_b32 s43, v4, 16
	v_readlane_b32 s52, v4, 48
	v_readlane_b32 s6, v4, 0
	v_readlane_b32 s7, v4, 32
	v_mov_b32_e32 v4, s43
	v_mov_b32_e32 v5, s52
	v_pk_add_f32 v[4:5], s[6:7], v[4:5]
	s_nop 0
	v_add_f32_e32 v4, v4, v5
	v_add_f32_e32 v8, 0x358637bd, v4
	v_pk_mul_f32 v[4:5], v[12:13], v[18:19]
	v_mul_f32_e32 v14, 0x4b800000, v8
	v_add_f32_e32 v4, v16, v4
	v_add_f32_e32 v4, v4, v5
	v_mul_f32_e32 v5, 0xbfb8aa3b, v4
	v_exp_f32_e32 v5, v5
	v_cmp_gt_f32_e32 vcc, s68, v8
	v_add_f32_e32 v16, v20, v21
	v_add_f32_e32 v0, 1.0, v5
	v_rcp_f32_e32 v0, v0
	v_cndmask_b32_e32 v8, v8, v14, vcc
	v_rsq_f32_e32 v8, v8
	v_mul_f32_e32 v0, v4, v0
	v_mul_f32_e32 v4, v0, v0
	v_mul_f32_e32 v5, 0x45800000, v8
	v_cndmask_b32_e32 v5, v8, v5, vcc
	v_mov_b32_dpp v4, v4 quad_perm:[1,0,3,2] row_mask:0xf bank_mask:0xf bound_ctrl:1
	v_fmac_f32_e32 v4, v0, v0
	v_mul_f32_e32 v6, v6, v5
	v_mov_b32_e32 v8, v19
	v_add_f32_dpp v4, v4, v4 quad_perm:[2,3,0,1] row_mask:0xf bank_mask:0xf bound_ctrl:1
	v_cvt_pk_bf16_f32 v6, v6, s0
	ds_write_b16 v44, v6 offset:9792
	v_add_f32_dpp v4, v4, v4 row_half_mirror row_mask:0xf bank_mask:0xf bound_ctrl:1
	v_pk_mul_f32 v[18:19], v[10:11], v[18:19]
	s_nop 0
	v_add_f32_dpp v4, v4, v4 row_mirror row_mask:0xf bank_mask:0xf bound_ctrl:1
	v_add_f32_e32 v18, v18, v19
	v_readlane_b32 s43, v4, 16
	v_readlane_b32 s52, v4, 48
	v_readlane_b32 s6, v4, 0
	v_readlane_b32 s7, v4, 32
	v_mov_b32_e32 v4, s43
	v_mov_b32_e32 v5, s52
	v_pk_add_f32 v[4:5], s[6:7], v[4:5]
	s_nop 0
	v_add_f32_e32 v4, v4, v5
	v_add_f32_e32 v4, 0x358637bd, v4
	v_mul_f32_e32 v5, 0x4b800000, v4
	v_cmp_gt_f32_e32 vcc, s68, v4
	s_nop 1
	v_cndmask_b32_e32 v4, v4, v5, vcc
	v_rsq_f32_e32 v14, v4
	v_pk_mul_f32 v[4:5], v[12:13], v[8:9]
	v_mul_f32_e32 v6, 0x45800000, v14
	v_add_f32_e32 v4, v16, v4
	v_add_f32_e32 v4, v4, v5
	v_mul_f32_e32 v5, 0xbfb8aa3b, v4
	v_exp_f32_e32 v5, v5
	v_cndmask_b32_e32 v6, v14, v6, vcc
	v_mul_f32_e32 v0, v0, v6
	v_mov_b32_e32 v6, v9
	v_add_f32_e32 v5, 1.0, v5
	v_rcp_f32_e32 v5, v5
	v_cvt_pk_bf16_f32 v0, v0, s0
	ds_write_b16 v44, v0 offset:9936
	v_pk_mul_f32 v[8:9], v[10:11], v[8:9]
	v_mul_f32_e32 v14, v4, v5
	v_mul_f32_e32 v4, v14, v14
	v_add_f32_e32 v8, v8, v9
	s_nop 0
	v_mov_b32_dpp v4, v4 quad_perm:[1,0,3,2] row_mask:0xf bank_mask:0xf bound_ctrl:1
	v_fmac_f32_e32 v4, v14, v14
	s_nop 1
	v_add_f32_dpp v4, v4, v4 quad_perm:[2,3,0,1] row_mask:0xf bank_mask:0xf bound_ctrl:1
	s_nop 1
	v_add_f32_dpp v4, v4, v4 row_half_mirror row_mask:0xf bank_mask:0xf bound_ctrl:1
	s_nop 1
	v_add_f32_dpp v4, v4, v4 row_mirror row_mask:0xf bank_mask:0xf bound_ctrl:1
	s_nop 0
	v_readlane_b32 s43, v4, 16
	v_readlane_b32 s52, v4, 48
	v_readlane_b32 s6, v4, 0
	v_readlane_b32 s7, v4, 32
	v_mov_b32_e32 v4, s43
	v_mov_b32_e32 v5, s52
	v_pk_add_f32 v[4:5], s[6:7], v[4:5]
	s_nop 0
	v_add_f32_e32 v4, v4, v5
	v_add_f32_e32 v16, 0x358637bd, v4
	v_pk_mul_f32 v[4:5], v[12:13], v[6:7]
	v_mul_f32_e32 v20, 0x4b800000, v16
	v_add_f32_e32 v4, v18, v4
	v_add_f32_e32 v4, v4, v5
	v_mul_f32_e32 v5, 0xbfb8aa3b, v4
	v_exp_f32_e32 v5, v5
	v_cmp_gt_f32_e32 vcc, s68, v16
	v_add_f32_e32 v0, 1.0, v5
	v_rcp_f32_e32 v0, v0
	v_cndmask_b32_e32 v16, v16, v20, vcc
	v_rsq_f32_e32 v16, v16
	v_mul_f32_e32 v0, v4, v0
	v_mul_f32_e32 v4, v0, v0
	v_mul_f32_e32 v5, 0x45800000, v16
	v_cndmask_b32_e32 v5, v16, v5, vcc
	v_mov_b32_dpp v4, v4 quad_perm:[1,0,3,2] row_mask:0xf bank_mask:0xf bound_ctrl:1
	v_fmac_f32_e32 v4, v0, v0
	v_mul_f32_e32 v14, v14, v5
	v_add_co_u32_e32 v20, vcc, 0x2000, v2
	v_add_f32_dpp v4, v4, v4 quad_perm:[2,3,0,1] row_mask:0xf bank_mask:0xf bound_ctrl:1
	s_nop 0
	v_addc_co_u32_e32 v21, vcc, 0, v3, vcc
	v_add_f32_dpp v4, v4, v4 row_half_mirror row_mask:0xf bank_mask:0xf bound_ctrl:1
	v_mov_b32_e32 v16, v7
	v_pk_mul_f32 v[18:19], v[12:13], v[16:17]
	v_add_f32_dpp v4, v4, v4 row_mirror row_mask:0xf bank_mask:0xf bound_ctrl:1
	v_add_f32_e32 v8, v8, v18
	v_readlane_b32 s43, v4, 16
	v_readlane_b32 s52, v4, 48
	v_readlane_b32 s6, v4, 0
	v_readlane_b32 s7, v4, 32
	v_mov_b32_e32 v4, s43
	v_mov_b32_e32 v5, s52
	v_pk_add_f32 v[4:5], s[6:7], v[4:5]
	v_add_f32_e32 v8, v8, v19
	v_add_f32_e32 v4, v4, v5
	v_add_f32_e32 v4, 0x358637bd, v4
	v_mul_f32_e32 v5, 0x4b800000, v4
	v_cmp_gt_f32_e64 s[6:7], s68, v4
	v_mul_f32_e32 v9, 0xbfb8aa3b, v8
	v_exp_f32_e32 v9, v9
	v_cndmask_b32_e64 v4, v4, v5, s[6:7]
	v_rsq_f32_e32 v22, v4
	v_lshl_add_u64 v[4:5], v[2:3], 0, s[64:65]
	global_load_dword v2, v[2:3], off offset:2048
	s_nop 0
	global_load_dword v5, v[4:5], off offset:3072
	s_nop 0
	global_load_dword v4, v[20:21], off
	global_load_dword v3, v[20:21], off offset:3072
	v_add_f32_e32 v9, 1.0, v9
	v_rcp_f32_e32 v9, v9
	v_cvt_pk_bf16_f32 v14, v14, s0
	ds_write_b16 v44, v14 offset:10080
	v_mul_f32_e32 v14, 0x45800000, v22
	v_mul_f32_e32 v16, v8, v9
	v_mul_f32_e32 v8, v16, v16
	v_cndmask_b32_e64 v14, v22, v14, s[6:7]
	v_mul_f32_e32 v0, v0, v14
	v_mov_b32_dpp v8, v8 quad_perm:[1,0,3,2] row_mask:0xf bank_mask:0xf bound_ctrl:1
	v_fmac_f32_e32 v8, v16, v16
	v_mov_b32_e32 v14, v17
	v_pk_mul_f32 v[6:7], v[10:11], v[6:7]
	v_add_f32_dpp v8, v8, v8 quad_perm:[2,3,0,1] row_mask:0xf bank_mask:0xf bound_ctrl:1
	v_add_f32_e32 v6, v6, v7
	v_cvt_pk_bf16_f32 v0, v0, s0
	v_add_f32_dpp v8, v8, v8 row_half_mirror row_mask:0xf bank_mask:0xf bound_ctrl:1
	ds_write_b16 v44, v0 offset:10224
	v_mov_b32_e32 v11, 0
	v_add_f32_dpp v8, v8, v8 row_mirror row_mask:0xf bank_mask:0xf bound_ctrl:1
	s_nop 0
	v_readlane_b32 s43, v8, 16
	v_readlane_b32 s52, v8, 48
	v_readlane_b32 s6, v8, 0
	v_readlane_b32 s7, v8, 32
	v_mov_b32_e32 v8, s43
	v_mov_b32_e32 v9, s52
	v_pk_add_f32 v[8:9], s[6:7], v[8:9]
	s_nop 0
	v_add_f32_e32 v8, v8, v9
	v_add_f32_e32 v18, 0x358637bd, v8
	v_pk_mul_f32 v[8:9], v[12:13], v[14:15]
	v_mul_f32_e32 v19, 0x4b800000, v18
	v_add_f32_e32 v6, v6, v8
	v_add_f32_e32 v6, v6, v9
	v_mul_f32_e32 v7, 0xbfb8aa3b, v6
	v_exp_f32_e32 v7, v7
	v_cmp_gt_f32_e32 vcc, s68, v18
	v_add_f32_e32 v7, 1.0, v7
	s_nop 0
	v_cndmask_b32_e32 v8, v18, v19, vcc
	v_rsq_f32_e32 v8, v8
	v_rcp_f32_e32 v7, v7
	v_mul_f32_e32 v0, 0x45800000, v8
	v_cndmask_b32_e32 v0, v8, v0, vcc
	v_mul_f32_e32 v8, v6, v7
	v_mul_f32_e32 v6, v8, v8
	v_mul_f32_e32 v0, v16, v0
	v_cvt_pk_bf16_f32 v0, v0, s0
	v_mov_b32_dpp v6, v6 quad_perm:[1,0,3,2] row_mask:0xf bank_mask:0xf bound_ctrl:1
	v_fmac_f32_e32 v6, v8, v8
	ds_write_b16 v44, v0 offset:10368
	s_nop 0
	v_add_f32_dpp v6, v6, v6 quad_perm:[2,3,0,1] row_mask:0xf bank_mask:0xf bound_ctrl:1
	s_nop 1
	v_add_f32_dpp v6, v6, v6 row_half_mirror row_mask:0xf bank_mask:0xf bound_ctrl:1
	s_nop 1
	v_add_f32_dpp v6, v6, v6 row_mirror row_mask:0xf bank_mask:0xf bound_ctrl:1
	s_nop 0
	v_readlane_b32 s43, v6, 16
	v_readlane_b32 s52, v6, 48
	v_readlane_b32 s6, v6, 0
	v_readlane_b32 s7, v6, 32
	v_mov_b32_e32 v6, s43
	v_mov_b32_e32 v7, s52
	v_pk_add_f32 v[6:7], s[6:7], v[6:7]
	s_nop 0
	v_add_f32_e32 v6, v6, v7
	v_add_f32_e32 v6, 0x358637bd, v6
	v_mul_f32_e32 v7, 0x4b800000, v6
	v_cmp_gt_f32_e32 vcc, s68, v6
	s_nop 1
	v_cndmask_b32_e32 v6, v6, v7, vcc
	v_rsq_f32_e32 v6, v6
	s_nop 0
	v_mul_f32_e32 v0, 0x45800000, v6
	v_cndmask_b32_e32 v0, v6, v0, vcc
	v_mul_f32_e32 v0, v8, v0
	v_cvt_pk_bf16_f32 v0, v0, s0
	ds_write_b16 v44, v0 offset:10512
	v_or_b32_e32 v0, 0x200, v50
	v_mov_b32_e32 v6, 0
	v_lshlrev_b32_e32 v0, 1, v0
	s_waitcnt vmcnt(24)
	s_and_saveexec_b64 s[6:7], s[10:11]
	s_cbranch_execz .LBB0_647
	v_mov_b32_e32 v11, v153
.LBB0_647:
	s_or_b64 exec, exec, s[6:7]
	s_and_saveexec_b64 s[6:7], s[18:19]
	s_cbranch_execz .LBB0_649
	v_mov_b32_e32 v6, v154
.LBB0_649:
	s_or_b64 exec, exec, s[6:7]
	v_mov_b32_e32 v7, 0
	v_mov_b32_e32 v13, 0
	s_and_saveexec_b64 s[6:7], s[20:21]
	s_cbranch_execz .LBB0_651
	v_mov_b32_e32 v13, v155
.LBB0_651:
	s_or_b64 exec, exec, s[6:7]
	s_and_saveexec_b64 s[6:7], s[22:23]
	s_cbranch_execz .LBB0_653
	v_mov_b32_e32 v7, v156
.LBB0_653:
	s_or_b64 exec, exec, s[6:7]
	v_mov_b32_e32 v8, 0
	v_mov_b32_e32 v15, 0
	s_and_saveexec_b64 s[6:7], s[24:25]
	s_cbranch_execz .LBB0_655
	v_mov_b32_e32 v15, v157
.LBB0_655:
	s_or_b64 exec, exec, s[6:7]
	s_and_saveexec_b64 s[6:7], s[26:27]
	s_cbranch_execz .LBB0_657
	v_mov_b32_e32 v8, v158
.LBB0_657:
	s_or_b64 exec, exec, s[6:7]
	v_mov_b32_e32 v9, 0
	v_mov_b32_e32 v17, 0
	s_and_saveexec_b64 s[6:7], s[28:29]
	s_cbranch_execz .LBB0_659
	v_mov_b32_e32 v17, v159
.LBB0_659:
	s_or_b64 exec, exec, s[6:7]
	s_and_saveexec_b64 s[6:7], s[30:31]
	s_cbranch_execz .LBB0_661
	v_mov_b32_e32 v9, v160
.LBB0_661:
	s_or_b64 exec, exec, s[6:7]
	v_mov_b32_e32 v10, 0
	v_mov_b32_e32 v18, 0
	s_and_saveexec_b64 s[6:7], s[34:35]
	s_cbranch_execz .LBB0_663
	v_mov_b32_e32 v18, v161
.LBB0_663:
	s_or_b64 exec, exec, s[6:7]
	s_and_saveexec_b64 s[6:7], s[36:37]
	s_cbranch_execz .LBB0_665
	v_mov_b32_e32 v10, v162
.LBB0_665:
	s_or_b64 exec, exec, s[6:7]
	v_mov_b32_e32 v12, 0
	v_mov_b32_e32 v19, 0
	s_and_saveexec_b64 s[6:7], s[38:39]
	s_cbranch_execz .LBB0_667
	v_mov_b32_e32 v19, v163
.LBB0_667:
	s_or_b64 exec, exec, s[6:7]
	s_and_saveexec_b64 s[6:7], s[44:45]
	s_cbranch_execz .LBB0_669
	v_mov_b32_e32 v12, v164
.LBB0_669:
	s_or_b64 exec, exec, s[6:7]
	v_mov_b32_e32 v14, 0
	v_mov_b32_e32 v20, 0
	s_and_saveexec_b64 s[6:7], s[48:49]
	s_cbranch_execz .LBB0_671
	v_mov_b32_e32 v20, v165
.LBB0_671:
	s_or_b64 exec, exec, s[6:7]
	s_and_saveexec_b64 s[6:7], s[50:51]
	s_cbranch_execz .LBB0_673
	v_mov_b32_e32 v14, v166
.LBB0_673:
	s_or_b64 exec, exec, s[6:7]
	v_mov_b32_e32 v16, 0
	v_mov_b32_e32 v21, 0
	s_and_saveexec_b64 s[6:7], s[56:57]
	s_cbranch_execz .LBB0_675
	v_mov_b32_e32 v21, v167
.LBB0_675:
	s_or_b64 exec, exec, s[6:7]
	s_and_saveexec_b64 s[6:7], s[58:59]
	s_cbranch_execz .LBB0_677
	v_mov_b32_e32 v16, v168

.LBB0_680:
	v_mov_b32_e32 v24, v171
.LBB0_681:
	s_or_b64 exec, exec, s[6:7]
	v_lshlrev_b32_e32 v11, 16, v11
	v_lshlrev_b32_e32 v6, 16, v6
	v_lshlrev_b32_e32 v13, 16, v13
	v_lshlrev_b32_e32 v7, 16, v7
	v_lshlrev_b32_e32 v15, 16, v15
	v_lshlrev_b32_e32 v8, 16, v8
	v_lshlrev_b32_e32 v17, 16, v17
	v_lshlrev_b32_e32 v9, 16, v9
	v_lshlrev_b32_e32 v18, 16, v18
	v_lshlrev_b32_e32 v10, 16, v10
	v_lshlrev_b32_e32 v19, 16, v19
	v_lshlrev_b32_e32 v12, 16, v12
	v_lshlrev_b32_e32 v20, 16, v20
	v_lshlrev_b32_e32 v14, 16, v14
	v_lshlrev_b32_e32 v21, 16, v21
	v_lshlrev_b32_e32 v16, 16, v16
	v_lshlrev_b32_e32 v24, 16, v24
	v_lshlrev_b32_e32 v23, 16, v23
	v_lshlrev_b32_e32 v22, 16, v22
	s_waitcnt vmcnt(2)
	v_mul_f32_e32 v0, v5, v6
	v_fmac_f32_e32 v0, v2, v11
	s_waitcnt vmcnt(1)
	v_fmac_f32_e32 v0, v4, v13
	v_mul_f32_e32 v25, v5, v13
	s_waitcnt vmcnt(0)
	v_fmac_f32_e32 v0, v3, v7
	v_fmac_f32_e32 v25, v2, v6
	v_mul_f32_e32 v11, 0xbfb8aa3b, v0
	v_fmac_f32_e32 v25, v4, v7
	v_exp_f32_e32 v11, v11
	v_fmac_f32_e32 v25, v3, v15
	v_mul_f32_e32 v6, 0xbfb8aa3b, v25
	v_exp_f32_e32 v6, v6
	v_add_f32_e32 v11, 1.0, v11
	v_rcp_f32_e32 v11, v11
	s_movk_i32 s6, 0x7f
	v_add_f32_e32 v6, 1.0, v6
	v_rcp_f32_e32 v6, v6
	v_mul_f32_e32 v0, v0, v11
	v_cvt_pk_bf16_f32 v0, v0, s0
	ds_write_b16 v43, v0 offset:18432
	v_mul_f32_e32 v0, v25, v6
	v_mul_f32_e32 v6, v5, v7
	v_fmac_f32_e32 v6, v2, v13
	v_fmac_f32_e32 v6, v4, v15
	v_fmac_f32_e32 v6, v3, v8
	v_mul_f32_e32 v11, 0xbfb8aa3b, v6
	v_exp_f32_e32 v11, v11
	v_mul_f32_e32 v13, v5, v15
	v_fmac_f32_e32 v13, v2, v7
	v_fmac_f32_e32 v13, v4, v8
	v_add_f32_e32 v11, 1.0, v11
	v_rcp_f32_e32 v11, v11
	v_fmac_f32_e32 v13, v3, v17
	v_mul_f32_e32 v7, 0xbfb8aa3b, v13
	v_exp_f32_e32 v7, v7
	v_mul_f32_e32 v6, v6, v11
	v_cvt_pk_bf16_f32 v6, v6, s0
	ds_write_b16 v42, v6 offset:18576
	v_mul_f32_e32 v6, v5, v8
	v_fmac_f32_e32 v6, v2, v15
	v_fmac_f32_e32 v6, v4, v17
	v_cvt_pk_bf16_f32 v0, v0, s0
	v_fmac_f32_e32 v6, v3, v9
	ds_write_b16 v42, v0 offset:18432
	v_add_f32_e32 v0, 1.0, v7
	v_mul_f32_e32 v7, 0xbfb8aa3b, v6
	v_exp_f32_e32 v7, v7
	v_mul_f32_e32 v11, v5, v17
	v_fmac_f32_e32 v11, v2, v8
	v_fmac_f32_e32 v11, v4, v9
	v_add_f32_e32 v7, 1.0, v7
	v_rcp_f32_e32 v7, v7
	v_rcp_f32_e32 v0, v0
	v_fmac_f32_e32 v11, v3, v18
	v_mul_f32_e32 v8, 0xbfb8aa3b, v11
	v_mul_f32_e32 v6, v6, v7
	v_cvt_pk_bf16_f32 v6, v6, s0
	ds_write_b16 v42, v6 offset:18864
	v_mul_f32_e32 v6, v5, v9
	v_fmac_f32_e32 v6, v2, v17
	v_fmac_f32_e32 v6, v4, v18
	v_fmac_f32_e32 v6, v3, v10
	v_mul_f32_e32 v7, 0xbfb8aa3b, v6
	v_exp_f32_e32 v8, v8
	v_exp_f32_e32 v7, v7
	v_mul_f32_e32 v0, v13, v0
	v_cvt_pk_bf16_f32 v0, v0, s0
	ds_write_b16 v42, v0 offset:18720
	v_add_f32_e32 v0, 1.0, v8
	v_add_f32_e32 v7, 1.0, v7
	v_rcp_f32_e32 v0, v0
	v_rcp_f32_e32 v7, v7
	v_mul_f32_e32 v8, v5, v18
	v_fmac_f32_e32 v8, v2, v9
	v_mul_f32_e32 v0, v11, v0
	v_mul_f32_e32 v6, v6, v7
	v_cvt_pk_bf16_f32 v0, v0, s0
	v_cvt_pk_bf16_f32 v6, v6, s0
	ds_write_b16 v42, v0 offset:19008
	ds_write_b16 v44, v6 offset:18432
	v_mul_f32_e32 v6, v5, v10
	v_fmac_f32_e32 v8, v4, v10
	v_fmac_f32_e32 v6, v2, v18
	v_fmac_f32_e32 v8, v3, v19
	v_fmac_f32_e32 v6, v4, v19
	v_mul_f32_e32 v9, 0xbfb8aa3b, v8
	v_fmac_f32_e32 v6, v3, v12
	v_exp_f32_e32 v9, v9
	v_mul_f32_e32 v7, 0xbfb8aa3b, v6
	v_exp_f32_e32 v7, v7
	s_lshl_b32 s18, s16, 1
	v_add_f32_e32 v0, 1.0, v9
	v_rcp_f32_e32 v0, v0
	v_add_f32_e32 v7, 1.0, v7
	v_rcp_f32_e32 v7, v7
	v_cmp_lt_i32_e64 s[6:7], s6, v47
	v_mul_f32_e32 v0, v8, v0
	v_mul_f32_e32 v8, v5, v19
	v_fmac_f32_e32 v8, v2, v10
	v_mul_f32_e32 v6, v6, v7
	v_fmac_f32_e32 v8, v4, v12
	v_cvt_pk_bf16_f32 v6, v6, s0
	v_fmac_f32_e32 v8, v3, v20
	ds_write_b16 v44, v6 offset:18720
	v_mul_f32_e32 v6, v5, v12
	v_mul_f32_e32 v9, 0xbfb8aa3b, v8
	v_fmac_f32_e32 v6, v2, v19
	v_exp_f32_e32 v9, v9
	v_fmac_f32_e32 v6, v4, v20
	v_fmac_f32_e32 v6, v3, v14
	v_mul_f32_e32 v7, 0xbfb8aa3b, v6
	v_cvt_pk_bf16_f32 v0, v0, s0
	v_exp_f32_e32 v7, v7
	ds_write_b16 v44, v0 offset:18576
	v_add_f32_e32 v0, 1.0, v9
	v_rcp_f32_e32 v0, v0
	v_add_f32_e32 v7, 1.0, v7
	v_rcp_f32_e32 v7, v7
	v_cmp_gt_i32_e32 vcc, s67, v47
	v_mul_f32_e32 v0, v8, v0
	v_mul_f32_e32 v8, v5, v20
	v_fmac_f32_e32 v8, v2, v12
	v_fmac_f32_e32 v8, v4, v14
	v_fmac_f32_e32 v8, v3, v21
	v_mul_f32_e32 v6, v6, v7
	v_mul_f32_e32 v9, 0xbfb8aa3b, v8
	v_cvt_pk_bf16_f32 v6, v6, s0
	v_exp_f32_e32 v9, v9
	ds_write_b16 v44, v6 offset:19008
	v_mul_f32_e32 v6, v5, v14
	v_fmac_f32_e32 v6, v2, v20
	v_fmac_f32_e32 v6, v4, v21
	v_cvt_pk_bf16_f32 v0, v0, s0
	v_fmac_f32_e32 v6, v3, v16
	ds_write_b16 v44, v0 offset:18864
	v_add_f32_e32 v0, 1.0, v9
	v_mul_f32_e32 v7, 0xbfb8aa3b, v6
	v_rcp_f32_e32 v0, v0
	v_exp_f32_e32 v7, v7
	v_mul_f32_e32 v0, v8, v0
	v_mul_f32_e32 v8, v5, v21
	v_add_f32_e32 v7, 1.0, v7
	v_fmac_f32_e32 v8, v2, v14
	v_rcp_f32_e32 v7, v7
	v_fmac_f32_e32 v8, v4, v16
	v_fmac_f32_e32 v8, v3, v23
	v_mul_f32_e32 v9, 0xbfb8aa3b, v8
	v_exp_f32_e32 v9, v9
	v_mul_f32_e32 v6, v6, v7
	v_cvt_pk_bf16_f32 v6, v6, s0
	ds_write_b16 v44, v6 offset:19296
	v_mul_f32_e32 v6, v5, v16
	v_mul_f32_e32 v5, v5, v23
	v_cvt_pk_bf16_f32 v0, v0, s0
	v_fmac_f32_e32 v6, v2, v21
	v_fmac_f32_e32 v5, v2, v16
	ds_write_b16 v44, v0 offset:19152
	v_add_f32_e32 v0, 1.0, v9
	v_fmac_f32_e32 v6, v4, v23
	v_fmac_f32_e32 v5, v4, v22
	v_rcp_f32_e32 v0, v0
	v_fmac_f32_e32 v6, v3, v22
	v_fmac_f32_e32 v5, v3, v24
	v_mul_f32_e32 v7, 0xbfb8aa3b, v6
	v_mul_f32_e32 v2, 0xbfb8aa3b, v5
	v_exp_f32_e32 v7, v7
	v_exp_f32_e32 v2, v2
	v_mul_f32_e32 v0, v8, v0
	v_cvt_pk_bf16_f32 v0, v0, s0
	v_add_f32_e32 v3, 1.0, v7
	ds_write_b16 v44, v0 offset:19440
	v_add_f32_e32 v0, 1.0, v2
	v_rcp_f32_e32 v3, v3
	v_rcp_f32_e32 v0, v0
	v_mul_f32_e32 v2, v6, v3
	v_mul_f32_e32 v0, v5, v0
	v_cvt_pk_bf16_f32 v2, v2, s0
	v_cvt_pk_bf16_f32 v0, v0, s0
	ds_write_b16 v44, v2 offset:19584
	ds_write_b16 v44, v0 offset:19728
	s_and_saveexec_b64 s[10:11], vcc
	s_cbranch_execz .LBB0_684
	v_xor_b32_e32 v0, 63, v46
	v_cmp_gt_u32_e32 vcc, 64, v47
	v_mov_b64_e32 v[2:3], s[8:9]
	s_load_dwordx4 s[20:23], s[0:1], 0xd0
	v_cndmask_b32_e32 v0, v0, v46, vcc
	v_or_b32_e32 v0, s53, v0
	v_mad_i64_i32 v[2:3], s[8:9], v0, s33, v[2:3]
	v_lshlrev_b32_e32 v0, 2, v49
	v_or_b32_e32 v8, s3, v0
	v_add_u32_e32 v4, 0xa00, v8
	v_ashrrev_i32_e32 v5, 31, v4
	s_or_b32 s19, s63, s3
	v_lshl_add_u64 v[4:5], v[4:5], 1, v[2:3]
	global_load_ushort v9, v[4:5], off
	v_add_u32_e32 v4, s19, v0
	v_ashrrev_i32_e32 v5, 31, v4
	v_lshlrev_b64 v[4:5], 2, v[4:5]
	s_waitcnt lgkmcnt(0)
	v_lshl_add_u64 v[6:7], s[22:23], 0, v[4:5]
	global_load_dword v0, v[6:7], off
	v_lshl_add_u64 v[4:5], s[20:21], 0, v[4:5]
	global_load_dword v6, v[4:5], off
	v_add_u32_e32 v4, 0xa08, v8
	v_ashrrev_i32_e32 v5, 31, v4
	v_lshl_add_u64 v[2:3], v[4:5], 1, v[2:3]
	global_load_ushort v3, v[2:3], off
	v_and_b32_e32 v4, 64, v190
	v_add_u32_e32 v2, -1, v190
	v_cmp_lt_i32_e32 vcc, v2, v4
	s_mov_b32 s3, 0x41a00000
	v_add_u32_e32 v5, -2, v190
	v_cndmask_b32_e32 v2, v2, v190, vcc
	v_lshlrev_b32_e32 v2, 2, v2
	v_add_u32_e32 v7, -4, v190
	v_cmp_lt_i32_e64 s[8:9], v7, v4
	v_add_u32_e32 v8, -8, v190
	v_add_u32_e32 v10, -16, v190
	v_subrev_u32_e32 v11, 32, v190
	s_mov_b64 s[20:21], 0x327800
	s_waitcnt vmcnt(3)
	v_lshlrev_b32_e32 v9, 16, v9
	s_waitcnt vmcnt(2)
	v_add_f32_e32 v0, v0, v9
	v_mul_f32_e32 v9, 0x3fb8aa3b, v0
	v_exp_f32_e32 v9, v9
	s_waitcnt vmcnt(1)
	v_mul_f32_e32 v6, 0x3fb8aa3b, v6
	v_exp_f32_e32 v6, v6
	v_add_f32_e32 v9, 1.0, v9
	v_cmp_gt_f32_e32 vcc, s68, v9
	s_waitcnt vmcnt(0)
	v_lshlrev_b32_e32 v3, 16, v3
	v_mul_f32_e32 v3, 0xbfb8aa3b, v3
	v_cndmask_b32_e64 v12, 0, 32, vcc
	v_ldexp_f32 v9, v9, v12
	v_log_f32_e32 v9, v9
	v_cndmask_b32_e32 v12, 0, v187, vcc
	v_mul_f32_e32 v13, 0x3f317217, v9
	v_fma_f32 v13, v9, s55, -v13
	v_fmac_f32_e32 v13, 0x3377d1cf, v9
	v_fmac_f32_e32 v13, 0x3f317217, v9
	v_cmp_lt_f32_e64 vcc, |v9|, s78
	s_nop 1
	v_cndmask_b32_e32 v9, v9, v13, vcc
	v_sub_f32_e32 v9, v9, v12
	v_cmp_lt_f32_e32 vcc, s3, v0
	v_lshl_add_u32 v12, v47, 2, 0
	s_nop 0
	v_cndmask_b32_e32 v0, v9, v0, vcc
	v_mul_f32_e64 v9, v0, -v6
	ds_bpermute_b32 v2, v2, v9
	v_cmp_lt_i32_e32 vcc, v5, v4
	s_waitcnt lgkmcnt(0)
	v_fma_f32 v0, v0, -v6, v2
	v_cndmask_b32_e32 v5, v5, v190, vcc
	v_cmp_eq_u32_e32 vcc, 0, v46
	v_lshlrev_b32_e32 v5, 2, v5
	v_cndmask_b32_e64 v6, v7, v190, s[8:9]
	v_cndmask_b32_e32 v0, v0, v9, vcc
	ds_bpermute_b32 v5, v5, v0
	v_cmp_gt_u32_e64 s[8:9], 2, v46
	v_lshlrev_b32_e32 v6, 2, v6
	v_add_u32_e32 v2, s18, v49
	s_waitcnt lgkmcnt(0)
	v_add_f32_e32 v5, v0, v5
	v_cndmask_b32_e64 v0, v5, v0, s[8:9]
	ds_bpermute_b32 v5, v6, v0
	v_cmp_lt_i32_e64 s[8:9], v8, v4
	s_waitcnt lgkmcnt(0)
	v_add_f32_e32 v5, v0, v5
	v_cndmask_b32_e64 v6, v8, v190, s[8:9]
	v_cmp_gt_u32_e64 s[8:9], 4, v46
	v_lshlrev_b32_e32 v6, 2, v6
	s_nop 0
	v_cndmask_b32_e64 v0, v5, v0, s[8:9]
	ds_bpermute_b32 v5, v6, v0
	v_cmp_lt_i32_e64 s[8:9], v10, v4
	s_waitcnt lgkmcnt(0)
	v_add_f32_e32 v5, v0, v5
	v_cndmask_b32_e64 v6, v10, v190, s[8:9]
	v_cmp_lt_i32_e64 s[8:9], v11, v4
	v_lshlrev_b32_e32 v6, 2, v6
	s_nop 0
	v_cndmask_b32_e64 v4, v11, v190, s[8:9]
	v_cmp_gt_u32_e64 s[8:9], 8, v46
	v_lshlrev_b32_e32 v4, 2, v4
	s_nop 0
	v_cndmask_b32_e64 v0, v5, v0, s[8:9]
	ds_bpermute_b32 v5, v6, v0
	v_exp_f32_e32 v6, v3
	v_cmp_gt_u32_e64 s[8:9], 16, v46
	s_waitcnt lgkmcnt(0)
	v_add_f32_e32 v3, v0, v5
	v_cndmask_b32_e64 v0, v3, v0, s[8:9]
	ds_bpermute_b32 v4, v4, v0
	v_cmp_gt_u32_e64 s[8:9], 32, v46
	v_add_f32_e32 v5, 1.0, v6
	v_rcp_f32_e32 v5, v5
	v_ashrrev_i32_e32 v3, 31, v2
	s_waitcnt lgkmcnt(0)
	v_add_f32_e32 v4, v0, v4
	v_cndmask_b32_e64 v0, v4, v0, s[8:9]
	ds_bpermute_b32 v4, v191, v0
	v_mul_f32_e32 v6, 0x3fb8aa3b, v0
	v_exp_f32_e32 v8, v6
	ds_write2st64_b32 v12, v0, v5 offset0:236 offset1:238
	ds_write_b32 v12, v8 offset:61440
	s_waitcnt lgkmcnt(2)
	v_sub_f32_e32 v0, v4, v0
	v_lshlrev_b64 v[2:3], 10, v[2:3]
	v_mul_f32_e32 v0, 0x3fb8aa3b, v0
	v_lshl_add_u64 v[2:3], s[4:5], 0, v[2:3]
	v_exp_f32_e32 v5, v0
	v_lshl_add_u64 v[2:3], v[2:3], 0, s[20:21]
	v_lshlrev_b32_e32 v0, 2, v46
	v_lshl_add_u64 v[6:7], v[2:3], 0, v[0:1]
	global_store_dword v[6:7], v8, off
	global_store_dword v[6:7], v5, off offset:256
	s_and_b64 exec, exec, vcc
	s_cbranch_execz .LBB0_684
	v_mul_f32_e32 v0, 0x3fb8aa3b, v4
	v_exp_f32_e32 v0, v0
	global_store_dword v[2:3], v0, off offset:512

.LBB0_759:
	v_mov_b32_e32 v23, v169
	s_or_b64 exec, exec, s[6:7]
	s_and_saveexec_b64 s[6:7], s[70:71]
	s_cbranch_execz .LBB0_679
.LBB0_760:
	v_mov_b32_e32 v22, v170
	s_or_b64 exec, exec, s[6:7]
	v_mov_b32_e32 v24, 0
	s_and_saveexec_b64 s[6:7], s[84:85]
	s_cbranch_execnz .LBB0_680
	s_branch .LBB0_681
